# GEMM K-loops: s_setprio 1 issued before the compute-phase barrier instead of after it (16 sites)
# speedup vs baseline: 1.0018x; 1.0018x over previous
; #define PG8_STAGE(bufoff, gbase, voff) do { _Pragma("unroll") for (int _i = 0; _i < 2; ++_i) \
;         __builtin_amdgcn_global_load_lds((const unsigned*)((const char*)(gbase) + (voff)[_i]), (PG8_LAS unsigned*)(lds + (bufoff) + ldsw + _i * 8192), 16, 0, 0); } while (0)
; #define PG8_LDA(dst, b, h) do { _Pragma("unroll") for (int m = 0; m < 4; ++m) _Pragma("unroll") for (int k = 0; k < 2; ++k) dst[m][k] = *(const PG8_LAS bf16x8*)(lds + PG8_SA(b, h) + aoff + m * 2048 + k * 1024); } while (0)
; #define PG8_LDB(dst, b, h) do { _Pragma("unroll") for (int n = 0; n < 2; ++n) _Pragma("unroll") for (int k = 0; k < 2; ++k) dst[n][k] = *(const PG8_LAS bf16x8*)(lds + PG8_SB(b, h) + boff + n * 2048 + k * 1024); } while (0)
; #define PG8_MMA(ai, bj, At, Bt) do { __builtin_amdgcn_s_setprio(1); _Pragma("unroll") for (int m = 0; m < 4; ++m) _Pragma("unroll") for (int n = 0; n < 2; ++n) _Pragma("unroll") for (int k = 0; k < 2; ++k) \
;         acc[ai][bj][m][n] = __builtin_amdgcn_mfma_f32_16x16x32_bf16(Bt[n][k], At[m][k], acc[ai][bj][m][n], 0, 0, 0); __builtin_amdgcn_s_setprio(0); } while (0)
; #define PG8_WAIT_V(n) asm volatile("s_waitcnt vmcnt(" #n ")" ::: "memory")
; #define PG8_WAIT_L(n) asm volatile("s_waitcnt lgkmcnt(" #n ")" ::: "memory")
; template <class Epi, class Sched, bool ALIGN_EPI = false, bool SP2 = false>
; __device__ __forceinline__ void gemm_phase(PG8_LAS unsigned char* lds, const Gemm g, const Sched& S, const Epi& E) {
;     ...
;             const bool last = (t == nt - 2);
;             const char* a1 = cA + (size_t)(t + 1) * kstep;
;             const char* a2 = last ? nA : cA + (size_t)(t + 2) * kstep; const char* b2 = last ? nB : cB + (size_t)(t + 2) * kstep;
;             const char* a3 = a2 + kstep; const char* b3 = b2 + kstep;
;             if (last && has_next) S.a_ready(nxt);
;             if constexpr (SP2) {
;             PG8_LDB(B0, 0, 0); PG8_LDB(B1, 0, 1); PG8_SCHED; PG8_LDA(At, 0, 0); PG8_STAGE(PG8_SA(1, 1), a1 + hstep, voffA);
;             PG8_WAIT_V(8); PG8_WAIT_L(0); PG8_BAR; PG8_MMA(0, 0, At, B0); PG8_MMA(0, 1, At, B1); PG8_BAR; PG8_SCHED;
;             PG8_LDA(At, 0, 1); PG8_STAGE(PG8_SB(0, 0), b2, voffB); PG8_STAGE(PG8_SB(0, 1), b2 + hstep, voffB); PG8_STAGE(PG8_SA(0, 0), a2, voffA);
;             PG8_WAIT_V(8); PG8_WAIT_L(0); PG8_BAR; PG8_MMA(1, 0, At, B0); PG8_MMA(1, 1, At, B1); PG8_BAR; PG8_SCHED;
.LBB0_66:
	s_add_u32 s34, s4, 0xfff80080
	s_addc_u32 s35, s5, -1
	s_add_i32 s95, 0, 0x10000
	s_cmp_eq_u32 s94, 28
	s_cselect_b32 s67, s49, s35
	s_cselect_b32 s66, s90, s34
	v_add_u32_e32 v142, s95, v148
	s_cselect_b32 s63, s43, s93
	s_cselect_b32 s62, s91, s92
	s_add_i32 s34, 0, 0x14000
	ds_read_b128 v[138:141], v142
	ds_read_b128 v[150:153], v142 offset:1024
	ds_read_b128 v[154:157], v142 offset:2048
	ds_read_b128 v[158:161], v142 offset:3072
	v_add_u32_e32 v142, s34, v148
	ds_read_b128 v[162:165], v142
	ds_read_b128 v[166:169], v142 offset:1024
	ds_read_b128 v[170:173], v142 offset:2048
	ds_read_b128 v[174:177], v142 offset:3072
	v_lshl_add_u64 v[142:143], s[4:5], 0, v[134:135]
	s_add_i32 m0, s80, 0xc000
	ds_read_b128 v[178:181], v149
	ds_read_b128 v[182:185], v149 offset:1024
	ds_read_b128 v[186:189], v149 offset:2048
	ds_read_b128 v[190:193], v149 offset:3072
	ds_read_b128 v[194:197], v149 offset:4096
	ds_read_b128 v[198:201], v149 offset:5120
	ds_read_b128 v[210:213], v149 offset:6144
	ds_read_b128 v[214:217], v149 offset:7168
	global_load_lds_dwordx4 v[142:143], off
	v_lshl_add_u64 v[142:143], s[4:5], 0, v[136:137]
	s_add_i32 m0, s80, 0xe000
	s_nop 0
	global_load_lds_dwordx4 v[142:143], off
	s_waitcnt vmcnt(8)
	s_waitcnt lgkmcnt(0)
	s_setprio 1
	s_barrier
	s_waitcnt lgkmcnt(0)
	v_mfma_f32_16x16x32_bf16 v[124:127], v[138:141], v[178:181], v[124:127]
	v_mfma_f32_16x16x32_bf16 v[120:123], v[154:157], v[178:181], v[120:123]
	v_mfma_f32_16x16x32_bf16 v[108:111], v[138:141], v[186:189], v[108:111]
	v_mfma_f32_16x16x32_bf16 v[104:107], v[154:157], v[186:189], v[104:107]
	v_mfma_f32_16x16x32_bf16 v[92:95], v[138:141], v[194:197], v[92:95]
	v_mfma_f32_16x16x32_bf16 v[88:91], v[154:157], v[194:197], v[88:91]
	v_mfma_f32_16x16x32_bf16 v[76:79], v[138:141], v[210:213], v[76:79]
	v_mfma_f32_16x16x32_bf16 v[72:75], v[154:157], v[210:213], v[72:75]
	v_mfma_f32_16x16x32_bf16 v[124:127], v[150:153], v[182:185], v[124:127]
	v_mfma_f32_16x16x32_bf16 v[120:123], v[158:161], v[182:185], v[120:123]
	v_mfma_f32_16x16x32_bf16 v[108:111], v[150:153], v[190:193], v[108:111]
	v_mfma_f32_16x16x32_bf16 v[104:107], v[158:161], v[190:193], v[104:107]
	v_mfma_f32_16x16x32_bf16 v[92:95], v[150:153], v[198:201], v[92:95]
	v_mfma_f32_16x16x32_bf16 v[88:91], v[158:161], v[198:201], v[88:91]
	v_mfma_f32_16x16x32_bf16 v[76:79], v[150:153], v[214:217], v[76:79]
	v_mfma_f32_16x16x32_bf16 v[72:75], v[158:161], v[214:217], v[72:75]
	s_setprio 0
	s_setprio 1
	v_mfma_f32_16x16x32_bf16 v[116:119], v[162:165], v[178:181], v[116:119]
	v_mfma_f32_16x16x32_bf16 v[112:115], v[170:173], v[178:181], v[112:115]
	v_mfma_f32_16x16x32_bf16 v[100:103], v[162:165], v[186:189], v[100:103]
	v_mfma_f32_16x16x32_bf16 v[96:99], v[170:173], v[186:189], v[96:99]
	v_mfma_f32_16x16x32_bf16 v[84:87], v[162:165], v[194:197], v[84:87]
	v_mfma_f32_16x16x32_bf16 v[80:83], v[170:173], v[194:197], v[80:83]
	v_mfma_f32_16x16x32_bf16 v[68:71], v[162:165], v[210:213], v[68:71]
	v_mfma_f32_16x16x32_bf16 v[64:67], v[170:173], v[210:213], v[64:67]
	v_mfma_f32_16x16x32_bf16 v[116:119], v[166:169], v[182:185], v[116:119]
	v_mfma_f32_16x16x32_bf16 v[112:115], v[174:177], v[182:185], v[112:115]
	v_mfma_f32_16x16x32_bf16 v[100:103], v[166:169], v[190:193], v[100:103]
	v_mfma_f32_16x16x32_bf16 v[96:99], v[174:177], v[190:193], v[96:99]
	v_mfma_f32_16x16x32_bf16 v[84:87], v[166:169], v[198:201], v[84:87]
	v_mfma_f32_16x16x32_bf16 v[80:83], v[174:177], v[198:201], v[80:83]
	v_mfma_f32_16x16x32_bf16 v[68:71], v[166:169], v[214:217], v[68:71]
	v_mfma_f32_16x16x32_bf16 v[64:67], v[174:177], v[214:217], v[64:67]
	s_setprio 0
	s_barrier
	s_add_i32 s35, s95, s79
	v_lshl_add_u64 v[142:143], s[62:63], 0, v[204:205]
	s_mov_b32 m0, s35
	ds_read_b128 v[178:181], v149 offset:16384
	ds_read_b128 v[182:185], v149 offset:17408
	ds_read_b128 v[186:189], v149 offset:18432
	ds_read_b128 v[190:193], v149 offset:19456
	ds_read_b128 v[194:197], v149 offset:20480
	ds_read_b128 v[198:201], v149 offset:21504
	ds_read_b128 v[210:213], v149 offset:22528
	ds_read_b128 v[214:217], v149 offset:23552
	global_load_lds_dwordx4 v[142:143], off
	s_add_i32 m0, s35, 0x2000
	s_add_u32 s96, s62, 0x80000
	v_lshl_add_u64 v[202:203], s[62:63], 0, v[128:129]
	s_addc_u32 s97, s63, 0
	s_add_i32 s34, s34, s79
	global_load_lds_dwordx4 v[202:203], off
	v_lshl_add_u64 v[206:207], s[96:97], 0, v[204:205]
	s_mov_b32 m0, s34
	v_lshl_add_u64 v[208:209], s[66:67], 0, v[130:131]
	global_load_lds_dwordx4 v[206:207], off
	v_lshl_add_u64 v[206:207], s[96:97], 0, v[128:129]
	s_add_i32 m0, s34, 0x2000
	s_nop 0
	global_load_lds_dwordx4 v[206:207], off
	v_lshl_add_u64 v[206:207], s[66:67], 0, v[132:133]
	s_mov_b32 m0, s80
	s_nop 0
	global_load_lds_dwordx4 v[206:207], off
	s_mov_b32 m0, s81
	s_nop 0
	global_load_lds_dwordx4 v[208:209], off
	s_waitcnt vmcnt(8)
	s_waitcnt lgkmcnt(0)
	s_setprio 1
	s_barrier
; #define PG8_STAGE(bufoff, gbase, voff) do { _Pragma("unroll") for (int _i = 0; _i < 2; ++_i) \
;         __builtin_amdgcn_global_load_lds((const unsigned*)((const char*)(gbase) + (voff)[_i]), (PG8_LAS unsigned*)(lds + (bufoff) + ldsw + _i * 8192), 16, 0, 0); } while (0)
; #define PG8_LDA(dst, b, h) do { _Pragma("unroll") for (int m = 0; m < 4; ++m) _Pragma("unroll") for (int k = 0; k < 2; ++k) dst[m][k] = *(const PG8_LAS bf16x8*)(lds + PG8_SA(b, h) + aoff + m * 2048 + k * 1024); } while (0)
; #define PG8_LDB(dst, b, h) do { _Pragma("unroll") for (int n = 0; n < 2; ++n) _Pragma("unroll") for (int k = 0; k < 2; ++k) dst[n][k] = *(const PG8_LAS bf16x8*)(lds + PG8_SB(b, h) + boff + n * 2048 + k * 1024); } while (0)
; #define PG8_MMA(ai, bj, At, Bt) do { __builtin_amdgcn_s_setprio(1); _Pragma("unroll") for (int m = 0; m < 4; ++m) _Pragma("unroll") for (int n = 0; n < 2; ++n) _Pragma("unroll") for (int k = 0; k < 2; ++k) \
;         acc[ai][bj][m][n] = __builtin_amdgcn_mfma_f32_16x16x32_bf16(Bt[n][k], At[m][k], acc[ai][bj][m][n], 0, 0, 0); __builtin_amdgcn_s_setprio(0); } while (0)
; #define PG8_WAIT_V(n) asm volatile("s_waitcnt vmcnt(" #n ")" ::: "memory")
; #define PG8_WAIT_L(n) asm volatile("s_waitcnt lgkmcnt(" #n ")" ::: "memory")
; #define PG8_BAR __builtin_amdgcn_s_barrier()
; #define PG8_SCHED __builtin_amdgcn_sched_barrier(0)
; template <class Epi, class Sched, bool ALIGN_EPI = false, bool SP2 = false>
; __device__ __forceinline__ void gemm_phase(PG8_LAS unsigned char* lds, const Gemm g, const Sched& S, const Epi& E) {
;     ...
;             PG8_WAIT_V(8); PG8_WAIT_L(0); PG8_BAR; PG8_MMA(1, 0, At, B0); PG8_MMA(1, 1, At, B1); PG8_BAR; PG8_SCHED;
;             PG8_LDB(B0, 1, 0); PG8_LDB(B1, 1, 1); PG8_SCHED; PG8_LDA(At, 1, 0); PG8_STAGE(PG8_SA(0, 1), a2 + hstep, voffA);
;             PG8_WAIT_V(8); PG8_WAIT_L(0); PG8_BAR; PG8_MMA(0, 0, At, B0); PG8_MMA(0, 1, At, B1); PG8_BAR; PG8_SCHED;
	s_waitcnt lgkmcnt(0)
	v_mfma_f32_16x16x32_bf16 v[60:63], v[138:141], v[178:181], v[60:63]
	v_mfma_f32_16x16x32_bf16 v[56:59], v[154:157], v[178:181], v[56:59]
	v_mfma_f32_16x16x32_bf16 v[44:47], v[138:141], v[186:189], v[44:47]
	v_mfma_f32_16x16x32_bf16 v[40:43], v[154:157], v[186:189], v[40:43]
	v_mfma_f32_16x16x32_bf16 v[28:31], v[138:141], v[194:197], v[28:31]
	v_mfma_f32_16x16x32_bf16 v[24:27], v[154:157], v[194:197], v[24:27]
	v_mfma_f32_16x16x32_bf16 v[12:15], v[138:141], v[210:213], v[12:15]
	v_mfma_f32_16x16x32_bf16 v[8:11], v[154:157], v[210:213], v[8:11]
	v_mfma_f32_16x16x32_bf16 v[60:63], v[150:153], v[182:185], v[60:63]
	v_mfma_f32_16x16x32_bf16 v[56:59], v[158:161], v[182:185], v[56:59]
	v_mfma_f32_16x16x32_bf16 v[44:47], v[150:153], v[190:193], v[44:47]
	v_mfma_f32_16x16x32_bf16 v[40:43], v[158:161], v[190:193], v[40:43]
	v_mfma_f32_16x16x32_bf16 v[28:31], v[150:153], v[198:201], v[28:31]
	v_mfma_f32_16x16x32_bf16 v[24:27], v[158:161], v[198:201], v[24:27]
	v_mfma_f32_16x16x32_bf16 v[12:15], v[150:153], v[214:217], v[12:15]
	v_mfma_f32_16x16x32_bf16 v[8:11], v[158:161], v[214:217], v[8:11]
	s_setprio 0
	s_setprio 1
	v_mfma_f32_16x16x32_bf16 v[52:55], v[162:165], v[178:181], v[52:55]
	v_mfma_f32_16x16x32_bf16 v[48:51], v[170:173], v[178:181], v[48:51]
	v_mfma_f32_16x16x32_bf16 v[36:39], v[162:165], v[186:189], v[36:39]
	v_mfma_f32_16x16x32_bf16 v[32:35], v[170:173], v[186:189], v[32:35]
	v_mfma_f32_16x16x32_bf16 v[20:23], v[162:165], v[194:197], v[20:23]
	v_mfma_f32_16x16x32_bf16 v[16:19], v[170:173], v[194:197], v[16:19]
	v_mfma_f32_16x16x32_bf16 v[4:7], v[162:165], v[210:213], v[4:7]
	v_mfma_f32_16x16x32_bf16 v[0:3], v[170:173], v[210:213], v[0:3]
	v_mfma_f32_16x16x32_bf16 v[52:55], v[166:169], v[182:185], v[52:55]
	v_mfma_f32_16x16x32_bf16 v[48:51], v[174:177], v[182:185], v[48:51]
	v_mfma_f32_16x16x32_bf16 v[36:39], v[166:169], v[190:193], v[36:39]
	v_mfma_f32_16x16x32_bf16 v[32:35], v[174:177], v[190:193], v[32:35]
	v_mfma_f32_16x16x32_bf16 v[20:23], v[166:169], v[198:201], v[20:23]
	v_mfma_f32_16x16x32_bf16 v[16:19], v[174:177], v[198:201], v[16:19]
	v_mfma_f32_16x16x32_bf16 v[4:7], v[166:169], v[214:217], v[4:7]
	v_mfma_f32_16x16x32_bf16 v[0:3], v[174:177], v[214:217], v[0:3]
	s_setprio 0
	s_barrier
	s_add_i32 s34, 0, 0x18000
	v_add_u32_e32 v144, s34, v148
	s_add_i32 s35, 0, 0x1c000
	ds_read_b128 v[138:141], v144
	ds_read_b128 v[150:153], v144 offset:1024
	ds_read_b128 v[154:157], v144 offset:2048
	ds_read_b128 v[158:161], v144 offset:3072
	v_add_u32_e32 v144, s35, v148
	ds_read_b128 v[162:165], v144
	ds_read_b128 v[166:169], v144 offset:1024
	ds_read_b128 v[170:173], v144 offset:2048
	ds_read_b128 v[174:177], v144 offset:3072
	s_add_u32 s66, s66, 0x80000
	s_addc_u32 s67, s67, 0
	s_mov_b32 m0, s82
	v_lshl_add_u64 v[218:219], s[66:67], 0, v[132:133]
	ds_read_b128 v[178:181], v149 offset:32768
	ds_read_b128 v[182:185], v149 offset:33792
	ds_read_b128 v[186:189], v149 offset:34816
	ds_read_b128 v[190:193], v149 offset:35840
	ds_read_b128 v[194:197], v149 offset:36864
	ds_read_b128 v[198:201], v149 offset:37888
	ds_read_b128 v[210:213], v149 offset:38912
	ds_read_b128 v[214:217], v149 offset:39936
	global_load_lds_dwordx4 v[218:219], off
	v_lshl_add_u64 v[218:219], s[66:67], 0, v[130:131]
	s_mov_b32 m0, s83
	s_nop 0
	global_load_lds_dwordx4 v[218:219], off
	s_waitcnt vmcnt(8)
	s_waitcnt lgkmcnt(0)
	s_setprio 1
	s_barrier
	s_waitcnt lgkmcnt(0)
	v_mfma_f32_16x16x32_bf16 v[124:127], v[138:141], v[178:181], v[124:127]
	v_mfma_f32_16x16x32_bf16 v[120:123], v[154:157], v[178:181], v[120:123]
	v_mfma_f32_16x16x32_bf16 v[108:111], v[138:141], v[186:189], v[108:111]
	v_mfma_f32_16x16x32_bf16 v[104:107], v[154:157], v[186:189], v[104:107]
	v_mfma_f32_16x16x32_bf16 v[92:95], v[138:141], v[194:197], v[92:95]
	v_mfma_f32_16x16x32_bf16 v[88:91], v[154:157], v[194:197], v[88:91]
	v_mfma_f32_16x16x32_bf16 v[76:79], v[138:141], v[210:213], v[76:79]
	v_mfma_f32_16x16x32_bf16 v[72:75], v[154:157], v[210:213], v[72:75]
	v_mfma_f32_16x16x32_bf16 v[124:127], v[150:153], v[182:185], v[124:127]
	v_mfma_f32_16x16x32_bf16 v[120:123], v[158:161], v[182:185], v[120:123]
	v_mfma_f32_16x16x32_bf16 v[108:111], v[150:153], v[190:193], v[108:111]
	v_mfma_f32_16x16x32_bf16 v[104:107], v[158:161], v[190:193], v[104:107]
	v_mfma_f32_16x16x32_bf16 v[92:95], v[150:153], v[198:201], v[92:95]
	v_mfma_f32_16x16x32_bf16 v[88:91], v[158:161], v[198:201], v[88:91]
	v_mfma_f32_16x16x32_bf16 v[76:79], v[150:153], v[214:217], v[76:79]
	v_mfma_f32_16x16x32_bf16 v[72:75], v[158:161], v[214:217], v[72:75]
	s_setprio 0
	s_setprio 1
	v_mfma_f32_16x16x32_bf16 v[116:119], v[162:165], v[178:181], v[116:119]
	v_mfma_f32_16x16x32_bf16 v[112:115], v[170:173], v[178:181], v[112:115]
	v_mfma_f32_16x16x32_bf16 v[100:103], v[162:165], v[186:189], v[100:103]
	v_mfma_f32_16x16x32_bf16 v[96:99], v[170:173], v[186:189], v[96:99]
	v_mfma_f32_16x16x32_bf16 v[84:87], v[162:165], v[194:197], v[84:87]
	v_mfma_f32_16x16x32_bf16 v[80:83], v[170:173], v[194:197], v[80:83]
	v_mfma_f32_16x16x32_bf16 v[68:71], v[162:165], v[210:213], v[68:71]
	v_mfma_f32_16x16x32_bf16 v[64:67], v[170:173], v[210:213], v[64:67]
	v_mfma_f32_16x16x32_bf16 v[116:119], v[166:169], v[182:185], v[116:119]
	v_mfma_f32_16x16x32_bf16 v[112:115], v[174:177], v[182:185], v[112:115]
	v_mfma_f32_16x16x32_bf16 v[100:103], v[166:169], v[190:193], v[100:103]
	v_mfma_f32_16x16x32_bf16 v[96:99], v[174:177], v[190:193], v[96:99]
	v_mfma_f32_16x16x32_bf16 v[84:87], v[166:169], v[198:201], v[84:87]
	v_mfma_f32_16x16x32_bf16 v[80:83], v[174:177], v[198:201], v[80:83]
	v_mfma_f32_16x16x32_bf16 v[68:71], v[166:169], v[214:217], v[68:71]
	v_mfma_f32_16x16x32_bf16 v[64:67], v[174:177], v[214:217], v[64:67]
	s_setprio 0
	s_barrier
; #define PG8_STAGE(bufoff, gbase, voff) do { _Pragma("unroll") for (int _i = 0; _i < 2; ++_i) \
;         __builtin_amdgcn_global_load_lds((const unsigned*)((const char*)(gbase) + (voff)[_i]), (PG8_LAS unsigned*)(lds + (bufoff) + ldsw + _i * 8192), 16, 0, 0); } while (0)
; #define PG8_LDA(dst, b, h) do { _Pragma("unroll") for (int m = 0; m < 4; ++m) _Pragma("unroll") for (int k = 0; k < 2; ++k) dst[m][k] = *(const PG8_LAS bf16x8*)(lds + PG8_SA(b, h) + aoff + m * 2048 + k * 1024); } while (0)
; #define PG8_MMA(ai, bj, At, Bt) do { __builtin_amdgcn_s_setprio(1); _Pragma("unroll") for (int m = 0; m < 4; ++m) _Pragma("unroll") for (int n = 0; n < 2; ++n) _Pragma("unroll") for (int k = 0; k < 2; ++k) \
;         acc[ai][bj][m][n] = __builtin_amdgcn_mfma_f32_16x16x32_bf16(Bt[n][k], At[m][k], acc[ai][bj][m][n], 0, 0, 0); __builtin_amdgcn_s_setprio(0); } while (0)
; #define PG8_WAIT_V(n) asm volatile("s_waitcnt vmcnt(" #n ")" ::: "memory")
; #define PG8_WAIT_L(n) asm volatile("s_waitcnt lgkmcnt(" #n ")" ::: "memory")
; #define PG8_BAR __builtin_amdgcn_s_barrier()
; #define PG8_SCHED __builtin_amdgcn_sched_barrier(0)
; template <class Epi, class Sched, bool ALIGN_EPI = false, bool SP2 = false>
; __device__ __forceinline__ void gemm_phase(PG8_LAS unsigned char* lds, const Gemm g, const Sched& S, const Epi& E) {
;     ...
;         for (int t = 0; t < nt; t += 2) {
;     ...
;             PG8_LDA(At, 1, 1); PG8_STAGE(PG8_SB(1, 0), b3, voffB); PG8_STAGE(PG8_SB(1, 1), b3 + hstep, voffB); PG8_STAGE(PG8_SA(1, 0), a3, voffA);
;             PG8_WAIT_V(8); PG8_WAIT_L(0); PG8_BAR; PG8_MMA(1, 0, At, B0); PG8_MMA(1, 1, At, B1); PG8_BAR; PG8_SCHED;
	s_add_i32 s34, s34, s79
	v_lshl_add_u64 v[142:143], v[142:143], 0, s[8:9]
	s_mov_b32 m0, s34
	ds_read_b128 v[178:181], v149 offset:49152
	ds_read_b128 v[182:185], v149 offset:50176
	ds_read_b128 v[186:189], v149 offset:51200
	ds_read_b128 v[190:193], v149 offset:52224
	ds_read_b128 v[194:197], v149 offset:53248
	ds_read_b128 v[198:201], v149 offset:54272
	ds_read_b128 v[210:213], v149 offset:55296
	ds_read_b128 v[214:217], v149 offset:56320
	global_load_lds_dwordx4 v[142:143], off
	s_add_i32 m0, s34, 0x2000
	s_add_u32 s62, s62, 0x80080
	v_lshl_add_u64 v[142:143], v[202:203], 0, s[8:9]
	s_addc_u32 s63, s63, 0
	s_add_i32 s34, s35, s79
	global_load_lds_dwordx4 v[142:143], off
	v_lshl_add_u64 v[142:143], s[62:63], 0, v[204:205]
	s_mov_b32 m0, s34
	s_nop 0
	global_load_lds_dwordx4 v[142:143], off
	v_lshl_add_u64 v[142:143], s[62:63], 0, v[128:129]
	s_add_i32 m0, s34, 0x2000
	s_nop 0
	global_load_lds_dwordx4 v[142:143], off
	v_lshl_add_u64 v[142:143], v[206:207], 0, s[8:9]
	s_mov_b32 m0, s85
	s_nop 0
	global_load_lds_dwordx4 v[142:143], off
	v_lshl_add_u64 v[142:143], v[208:209], 0, s[8:9]
	s_mov_b32 m0, s86
	s_nop 0
	global_load_lds_dwordx4 v[142:143], off
	s_waitcnt vmcnt(8)
	s_waitcnt lgkmcnt(0)
	s_setprio 1
	s_barrier
	s_waitcnt lgkmcnt(0)
	v_mfma_f32_16x16x32_bf16 v[60:63], v[138:141], v[178:181], v[60:63]
	v_mfma_f32_16x16x32_bf16 v[56:59], v[154:157], v[178:181], v[56:59]
	v_mfma_f32_16x16x32_bf16 v[44:47], v[138:141], v[186:189], v[44:47]
	v_mfma_f32_16x16x32_bf16 v[40:43], v[154:157], v[186:189], v[40:43]
	v_mfma_f32_16x16x32_bf16 v[28:31], v[138:141], v[194:197], v[28:31]
	v_mfma_f32_16x16x32_bf16 v[24:27], v[154:157], v[194:197], v[24:27]
	v_mfma_f32_16x16x32_bf16 v[12:15], v[138:141], v[210:213], v[12:15]
	v_mfma_f32_16x16x32_bf16 v[8:11], v[154:157], v[210:213], v[8:11]
	v_mfma_f32_16x16x32_bf16 v[60:63], v[150:153], v[182:185], v[60:63]
	v_mfma_f32_16x16x32_bf16 v[56:59], v[158:161], v[182:185], v[56:59]
	v_mfma_f32_16x16x32_bf16 v[44:47], v[150:153], v[190:193], v[44:47]
	v_mfma_f32_16x16x32_bf16 v[40:43], v[158:161], v[190:193], v[40:43]
	v_mfma_f32_16x16x32_bf16 v[28:31], v[150:153], v[198:201], v[28:31]
	v_mfma_f32_16x16x32_bf16 v[24:27], v[158:161], v[198:201], v[24:27]
	v_mfma_f32_16x16x32_bf16 v[12:15], v[150:153], v[214:217], v[12:15]
	v_mfma_f32_16x16x32_bf16 v[8:11], v[158:161], v[214:217], v[8:11]
	s_setprio 0
	s_setprio 1
	v_mfma_f32_16x16x32_bf16 v[52:55], v[162:165], v[178:181], v[52:55]
	v_mfma_f32_16x16x32_bf16 v[48:51], v[170:173], v[178:181], v[48:51]
	v_mfma_f32_16x16x32_bf16 v[36:39], v[162:165], v[186:189], v[36:39]
	v_mfma_f32_16x16x32_bf16 v[32:35], v[170:173], v[186:189], v[32:35]
	v_mfma_f32_16x16x32_bf16 v[20:23], v[162:165], v[194:197], v[20:23]
	v_mfma_f32_16x16x32_bf16 v[16:19], v[170:173], v[194:197], v[16:19]
	v_mfma_f32_16x16x32_bf16 v[4:7], v[162:165], v[210:213], v[4:7]
	v_mfma_f32_16x16x32_bf16 v[0:3], v[170:173], v[210:213], v[0:3]
	v_mfma_f32_16x16x32_bf16 v[52:55], v[166:169], v[182:185], v[52:55]
	v_mfma_f32_16x16x32_bf16 v[48:51], v[174:177], v[182:185], v[48:51]
	v_mfma_f32_16x16x32_bf16 v[36:39], v[166:169], v[190:193], v[36:39]
	v_mfma_f32_16x16x32_bf16 v[32:35], v[174:177], v[190:193], v[32:35]
	v_mfma_f32_16x16x32_bf16 v[20:23], v[166:169], v[198:201], v[20:23]
	v_mfma_f32_16x16x32_bf16 v[16:19], v[174:177], v[198:201], v[16:19]
	v_mfma_f32_16x16x32_bf16 v[4:7], v[166:169], v[214:217], v[4:7]
	v_mfma_f32_16x16x32_bf16 v[0:3], v[174:177], v[214:217], v[0:3]
	s_setprio 0
	s_barrier
	s_add_i32 s94, s94, 2
	s_add_u32 s4, s4, 0x100
	s_addc_u32 s5, s5, 0
	s_add_u32 s92, s92, 0x100
	s_addc_u32 s93, s93, 0
	s_cmp_gt_u32 s94, 29
	s_cbranch_scc0 .LBB0_66
	s_and_b64 vcc, exec, s[18:19]
	s_cbranch_vccz .LBB0_69
	s_barrier

; #define PG8_STAGE(bufoff, gbase, voff) do { _Pragma("unroll") for (int _i = 0; _i < 2; ++_i) \
;         __builtin_amdgcn_global_load_lds((const unsigned*)((const char*)(gbase) + (voff)[_i]), (PG8_LAS unsigned*)(lds + (bufoff) + ldsw + _i * 8192), 16, 0, 0); } while (0)
; #define PG8_LDA(dst, b, h) do { _Pragma("unroll") for (int m = 0; m < 4; ++m) _Pragma("unroll") for (int k = 0; k < 2; ++k) dst[m][k] = *(const PG8_LAS bf16x8*)(lds + PG8_SA(b, h) + aoff + m * 2048 + k * 1024); } while (0)
; #define PG8_LDB(dst, b, h) do { _Pragma("unroll") for (int n = 0; n < 2; ++n) _Pragma("unroll") for (int k = 0; k < 2; ++k) dst[n][k] = *(const PG8_LAS bf16x8*)(lds + PG8_SB(b, h) + boff + n * 2048 + k * 1024); } while (0)
; #define PG8_MMA(ai, bj, At, Bt) do { __builtin_amdgcn_s_setprio(1); _Pragma("unroll") for (int m = 0; m < 4; ++m) _Pragma("unroll") for (int n = 0; n < 2; ++n) _Pragma("unroll") for (int k = 0; k < 2; ++k) \
;         acc[ai][bj][m][n] = __builtin_amdgcn_mfma_f32_16x16x32_bf16(Bt[n][k], At[m][k], acc[ai][bj][m][n], 0, 0, 0); __builtin_amdgcn_s_setprio(0); } while (0)
; #define PG8_WAIT_V(n) asm volatile("s_waitcnt vmcnt(" #n ")" ::: "memory")
; #define PG8_WAIT_L(n) asm volatile("s_waitcnt lgkmcnt(" #n ")" ::: "memory")
; template <class Epi, class Sched, bool ALIGN_EPI = false, bool SP2 = false>
; __device__ __forceinline__ void gemm_phase(PG8_LAS unsigned char* lds, const Gemm g, const Sched& S, const Epi& E) {
;     ...
;             const bool last = (t == nt - 2);
;             const char* a1 = cA + (size_t)(t + 1) * kstep;
;             const char* a2 = last ? nA : cA + (size_t)(t + 2) * kstep; const char* b2 = last ? nB : cB + (size_t)(t + 2) * kstep;
;             const char* a3 = a2 + kstep; const char* b3 = b2 + kstep;
;             if (last && has_next) S.a_ready(nxt);
;             if constexpr (SP2) {
;             PG8_LDB(B0, 0, 0); PG8_LDB(B1, 0, 1); PG8_SCHED; PG8_LDA(At, 0, 0); PG8_STAGE(PG8_SA(1, 1), a1 + hstep, voffA);
;             PG8_WAIT_V(8); PG8_WAIT_L(0); PG8_BAR; PG8_MMA(0, 0, At, B0); PG8_MMA(0, 1, At, B1); PG8_BAR; PG8_SCHED;
;             PG8_LDA(At, 0, 1); PG8_STAGE(PG8_SB(0, 0), b2, voffB); PG8_STAGE(PG8_SB(0, 1), b2 + hstep, voffB); PG8_STAGE(PG8_SA(0, 0), a2, voffA);
;             PG8_WAIT_V(8); PG8_WAIT_L(0); PG8_BAR; PG8_MMA(1, 0, At, B0); PG8_MMA(1, 1, At, B1); PG8_BAR; PG8_SCHED;
.LBB0_311:
	s_add_u32 s34, s6, 0xfff80080
	s_addc_u32 s35, s7, -1
	s_add_i32 s72, 0, 0x10000
	s_cmp_eq_u32 vcc_hi, 28
	s_cselect_b32 s67, s57, s35
	s_cselect_b32 s66, s93, s34
	s_cselect_b32 s63, s95, vcc_lo
	s_cselect_b32 s62, s98, s99
	s_add_i32 s74, 0, 0x14000
	v_add_u32_e32 v76, s72, v240
	v_add_u32_e32 v156, s74, v240
	ds_read_b128 v[64:67], v76
	ds_read_b128 v[68:71], v76 offset:1024
	ds_read_b128 v[72:75], v76 offset:2048
	ds_read_b128 v[76:79], v76 offset:3072
	ds_read_b128 v[144:147], v156
	ds_read_b128 v[148:151], v156 offset:1024
	ds_read_b128 v[152:155], v156 offset:2048
	ds_read_b128 v[156:159], v156 offset:3072
	v_lshl_add_u64 v[192:193], s[6:7], 0, v[216:217]
	s_add_i32 m0, s80, 0xc000
	ds_read_b128 v[160:163], v241
	ds_read_b128 v[164:167], v241 offset:1024
	ds_read_b128 v[168:171], v241 offset:2048
	ds_read_b128 v[172:175], v241 offset:3072
	ds_read_b128 v[176:179], v241 offset:4096
	ds_read_b128 v[180:183], v241 offset:5120
	ds_read_b128 v[184:187], v241 offset:6144
	ds_read_b128 v[188:191], v241 offset:7168
	global_load_lds_dwordx4 v[192:193], off
	v_lshl_add_u64 v[192:193], s[6:7], 0, v[218:219]
	s_add_i32 m0, s80, 0xe000
	s_nop 0
	global_load_lds_dwordx4 v[192:193], off
	s_waitcnt vmcnt(8)
	s_waitcnt lgkmcnt(0)
	s_setprio 1
	s_barrier
	s_waitcnt lgkmcnt(0)
	v_mfma_f32_16x16x32_bf16 v[140:143], v[64:67], v[160:163], v[140:143]
	v_mfma_f32_16x16x32_bf16 v[136:139], v[72:75], v[160:163], v[136:139]
	v_mfma_f32_16x16x32_bf16 v[124:127], v[64:67], v[168:171], v[124:127]
	v_mfma_f32_16x16x32_bf16 v[120:123], v[72:75], v[168:171], v[120:123]
	v_mfma_f32_16x16x32_bf16 v[108:111], v[64:67], v[176:179], v[108:111]
	v_mfma_f32_16x16x32_bf16 v[104:107], v[72:75], v[176:179], v[104:107]
	v_mfma_f32_16x16x32_bf16 v[92:95], v[64:67], v[184:187], v[92:95]
	v_mfma_f32_16x16x32_bf16 v[88:91], v[72:75], v[184:187], v[88:91]
	v_mfma_f32_16x16x32_bf16 v[140:143], v[68:71], v[164:167], v[140:143]
	v_mfma_f32_16x16x32_bf16 v[136:139], v[76:79], v[164:167], v[136:139]
	v_mfma_f32_16x16x32_bf16 v[124:127], v[68:71], v[172:175], v[124:127]
	v_mfma_f32_16x16x32_bf16 v[120:123], v[76:79], v[172:175], v[120:123]
	v_mfma_f32_16x16x32_bf16 v[108:111], v[68:71], v[180:183], v[108:111]
	v_mfma_f32_16x16x32_bf16 v[104:107], v[76:79], v[180:183], v[104:107]
	v_mfma_f32_16x16x32_bf16 v[92:95], v[68:71], v[188:191], v[92:95]
	v_mfma_f32_16x16x32_bf16 v[88:91], v[76:79], v[188:191], v[88:91]
	s_setprio 0
	s_setprio 1
	v_mfma_f32_16x16x32_bf16 v[132:135], v[144:147], v[160:163], v[132:135]
	v_mfma_f32_16x16x32_bf16 v[128:131], v[152:155], v[160:163], v[128:131]
	v_mfma_f32_16x16x32_bf16 v[116:119], v[144:147], v[168:171], v[116:119]
	v_mfma_f32_16x16x32_bf16 v[112:115], v[152:155], v[168:171], v[112:115]
	v_mfma_f32_16x16x32_bf16 v[100:103], v[144:147], v[176:179], v[100:103]
	v_mfma_f32_16x16x32_bf16 v[96:99], v[152:155], v[176:179], v[96:99]
	v_mfma_f32_16x16x32_bf16 v[84:87], v[144:147], v[184:187], v[84:87]
	v_mfma_f32_16x16x32_bf16 v[80:83], v[152:155], v[184:187], v[80:83]
	v_mfma_f32_16x16x32_bf16 v[132:135], v[148:151], v[164:167], v[132:135]
	v_mfma_f32_16x16x32_bf16 v[128:131], v[156:159], v[164:167], v[128:131]
	v_mfma_f32_16x16x32_bf16 v[116:119], v[148:151], v[172:175], v[116:119]
	v_mfma_f32_16x16x32_bf16 v[112:115], v[156:159], v[172:175], v[112:115]
	v_mfma_f32_16x16x32_bf16 v[100:103], v[148:151], v[180:183], v[100:103]
	v_mfma_f32_16x16x32_bf16 v[96:99], v[156:159], v[180:183], v[96:99]
	v_mfma_f32_16x16x32_bf16 v[84:87], v[148:151], v[188:191], v[84:87]
	v_mfma_f32_16x16x32_bf16 v[80:83], v[156:159], v[188:191], v[80:83]
	s_setprio 0
	s_barrier
	s_add_i32 s34, s72, s79
	v_lshl_add_u64 v[192:193], s[62:63], 0, v[204:205]
	s_mov_b32 m0, s34
	ds_read_b128 v[160:163], v241 offset:16384
	ds_read_b128 v[164:167], v241 offset:17408
	ds_read_b128 v[168:171], v241 offset:18432
	ds_read_b128 v[172:175], v241 offset:19456
	ds_read_b128 v[176:179], v241 offset:20480
	ds_read_b128 v[180:183], v241 offset:21504
	ds_read_b128 v[184:187], v241 offset:22528
	ds_read_b128 v[188:191], v241 offset:23552
	global_load_lds_dwordx4 v[192:193], off
	s_add_i32 m0, s34, 0x2000
	s_add_u32 s34, s62, 0x80000
	v_lshl_add_u64 v[194:195], s[62:63], 0, v[210:211]
	s_addc_u32 s35, s63, 0
	s_add_i32 s72, s74, s79
	global_load_lds_dwordx4 v[194:195], off
	v_lshl_add_u64 v[196:197], s[34:35], 0, v[204:205]
	s_mov_b32 m0, s72
	v_lshl_add_u64 v[198:199], s[66:67], 0, v[212:213]
	global_load_lds_dwordx4 v[196:197], off
	v_lshl_add_u64 v[196:197], s[34:35], 0, v[210:211]
	s_add_i32 m0, s72, 0x2000
	s_nop 0
	global_load_lds_dwordx4 v[196:197], off
	v_lshl_add_u64 v[196:197], s[66:67], 0, v[214:215]
	s_mov_b32 m0, s80
	s_nop 0
	global_load_lds_dwordx4 v[196:197], off
	s_mov_b32 m0, s81
	s_nop 0
	global_load_lds_dwordx4 v[198:199], off
	s_waitcnt vmcnt(8)
	s_waitcnt lgkmcnt(0)
	s_setprio 1
	s_barrier
; #define PG8_STAGE(bufoff, gbase, voff) do { _Pragma("unroll") for (int _i = 0; _i < 2; ++_i) \
;         __builtin_amdgcn_global_load_lds((const unsigned*)((const char*)(gbase) + (voff)[_i]), (PG8_LAS unsigned*)(lds + (bufoff) + ldsw + _i * 8192), 16, 0, 0); } while (0)
; #define PG8_LDA(dst, b, h) do { _Pragma("unroll") for (int m = 0; m < 4; ++m) _Pragma("unroll") for (int k = 0; k < 2; ++k) dst[m][k] = *(const PG8_LAS bf16x8*)(lds + PG8_SA(b, h) + aoff + m * 2048 + k * 1024); } while (0)
; #define PG8_LDB(dst, b, h) do { _Pragma("unroll") for (int n = 0; n < 2; ++n) _Pragma("unroll") for (int k = 0; k < 2; ++k) dst[n][k] = *(const PG8_LAS bf16x8*)(lds + PG8_SB(b, h) + boff + n * 2048 + k * 1024); } while (0)
; #define PG8_MMA(ai, bj, At, Bt) do { __builtin_amdgcn_s_setprio(1); _Pragma("unroll") for (int m = 0; m < 4; ++m) _Pragma("unroll") for (int n = 0; n < 2; ++n) _Pragma("unroll") for (int k = 0; k < 2; ++k) \
;         acc[ai][bj][m][n] = __builtin_amdgcn_mfma_f32_16x16x32_bf16(Bt[n][k], At[m][k], acc[ai][bj][m][n], 0, 0, 0); __builtin_amdgcn_s_setprio(0); } while (0)
; #define PG8_WAIT_V(n) asm volatile("s_waitcnt vmcnt(" #n ")" ::: "memory")
; #define PG8_WAIT_L(n) asm volatile("s_waitcnt lgkmcnt(" #n ")" ::: "memory")
; #define PG8_BAR __builtin_amdgcn_s_barrier()
; #define PG8_SCHED __builtin_amdgcn_sched_barrier(0)
; template <class Epi, class Sched, bool ALIGN_EPI = false, bool SP2 = false>
; __device__ __forceinline__ void gemm_phase(PG8_LAS unsigned char* lds, const Gemm g, const Sched& S, const Epi& E) {
;     ...
;             PG8_WAIT_V(8); PG8_WAIT_L(0); PG8_BAR; PG8_MMA(1, 0, At, B0); PG8_MMA(1, 1, At, B1); PG8_BAR; PG8_SCHED;
;             PG8_LDB(B0, 1, 0); PG8_LDB(B1, 1, 1); PG8_SCHED; PG8_LDA(At, 1, 0); PG8_STAGE(PG8_SA(0, 1), a2 + hstep, voffA);
;             PG8_WAIT_V(8); PG8_WAIT_L(0); PG8_BAR; PG8_MMA(0, 0, At, B0); PG8_MMA(0, 1, At, B1); PG8_BAR; PG8_SCHED;
	s_waitcnt lgkmcnt(0)
	v_mfma_f32_16x16x32_bf16 v[60:63], v[64:67], v[160:163], v[60:63]
	v_mfma_f32_16x16x32_bf16 v[56:59], v[72:75], v[160:163], v[56:59]
	v_mfma_f32_16x16x32_bf16 v[44:47], v[64:67], v[168:171], v[44:47]
	v_mfma_f32_16x16x32_bf16 v[40:43], v[72:75], v[168:171], v[40:43]
	v_mfma_f32_16x16x32_bf16 v[28:31], v[64:67], v[176:179], v[28:31]
	v_mfma_f32_16x16x32_bf16 v[24:27], v[72:75], v[176:179], v[24:27]
	v_mfma_f32_16x16x32_bf16 v[12:15], v[64:67], v[184:187], v[12:15]
	v_mfma_f32_16x16x32_bf16 v[8:11], v[72:75], v[184:187], v[8:11]
	v_mfma_f32_16x16x32_bf16 v[60:63], v[68:71], v[164:167], v[60:63]
	v_mfma_f32_16x16x32_bf16 v[56:59], v[76:79], v[164:167], v[56:59]
	v_mfma_f32_16x16x32_bf16 v[44:47], v[68:71], v[172:175], v[44:47]
	v_mfma_f32_16x16x32_bf16 v[40:43], v[76:79], v[172:175], v[40:43]
	v_mfma_f32_16x16x32_bf16 v[28:31], v[68:71], v[180:183], v[28:31]
	v_mfma_f32_16x16x32_bf16 v[24:27], v[76:79], v[180:183], v[24:27]
	v_mfma_f32_16x16x32_bf16 v[12:15], v[68:71], v[188:191], v[12:15]
	v_mfma_f32_16x16x32_bf16 v[8:11], v[76:79], v[188:191], v[8:11]
	s_setprio 0
	s_setprio 1
	v_mfma_f32_16x16x32_bf16 v[52:55], v[144:147], v[160:163], v[52:55]
	v_mfma_f32_16x16x32_bf16 v[48:51], v[152:155], v[160:163], v[48:51]
	v_mfma_f32_16x16x32_bf16 v[36:39], v[144:147], v[168:171], v[36:39]
	v_mfma_f32_16x16x32_bf16 v[32:35], v[152:155], v[168:171], v[32:35]
	v_mfma_f32_16x16x32_bf16 v[20:23], v[144:147], v[176:179], v[20:23]
	v_mfma_f32_16x16x32_bf16 v[16:19], v[152:155], v[176:179], v[16:19]
	v_mfma_f32_16x16x32_bf16 v[4:7], v[144:147], v[184:187], v[4:7]
	v_mfma_f32_16x16x32_bf16 v[0:3], v[152:155], v[184:187], v[0:3]
	v_mfma_f32_16x16x32_bf16 v[52:55], v[148:151], v[164:167], v[52:55]
	v_mfma_f32_16x16x32_bf16 v[48:51], v[156:159], v[164:167], v[48:51]
	v_mfma_f32_16x16x32_bf16 v[36:39], v[148:151], v[172:175], v[36:39]
	v_mfma_f32_16x16x32_bf16 v[32:35], v[156:159], v[172:175], v[32:35]
	v_mfma_f32_16x16x32_bf16 v[20:23], v[148:151], v[180:183], v[20:23]
	v_mfma_f32_16x16x32_bf16 v[16:19], v[156:159], v[180:183], v[16:19]
	v_mfma_f32_16x16x32_bf16 v[4:7], v[148:151], v[188:191], v[4:7]
	v_mfma_f32_16x16x32_bf16 v[0:3], v[156:159], v[188:191], v[0:3]
	s_setprio 0
	s_barrier
	s_add_i32 s72, 0, 0x18000
	s_add_i32 s74, 0, 0x1c000
	v_add_u32_e32 v76, s72, v240
	v_add_u32_e32 v156, s74, v240
	ds_read_b128 v[64:67], v76
	ds_read_b128 v[68:71], v76 offset:1024
	ds_read_b128 v[72:75], v76 offset:2048
	ds_read_b128 v[76:79], v76 offset:3072
	ds_read_b128 v[144:147], v156
	ds_read_b128 v[148:151], v156 offset:1024
	ds_read_b128 v[152:155], v156 offset:2048
	ds_read_b128 v[156:159], v156 offset:3072
	s_add_u32 s34, s66, 0x80000
	s_addc_u32 s35, s67, 0
	s_mov_b32 m0, s82
	v_lshl_add_u64 v[200:201], s[34:35], 0, v[214:215]
	ds_read_b128 v[160:163], v241 offset:32768
	ds_read_b128 v[164:167], v241 offset:33792
	ds_read_b128 v[168:171], v241 offset:34816
	ds_read_b128 v[172:175], v241 offset:35840
	ds_read_b128 v[176:179], v241 offset:36864
	ds_read_b128 v[180:183], v241 offset:37888
	ds_read_b128 v[184:187], v241 offset:38912
	ds_read_b128 v[188:191], v241 offset:39936
	global_load_lds_dwordx4 v[200:201], off
	v_lshl_add_u64 v[200:201], s[34:35], 0, v[212:213]
	s_mov_b32 m0, s83
	s_nop 0
	global_load_lds_dwordx4 v[200:201], off
	s_waitcnt vmcnt(8)
	s_waitcnt lgkmcnt(0)
	s_setprio 1
	s_barrier
	s_waitcnt lgkmcnt(0)
	v_mfma_f32_16x16x32_bf16 v[140:143], v[64:67], v[160:163], v[140:143]
	v_mfma_f32_16x16x32_bf16 v[136:139], v[72:75], v[160:163], v[136:139]
	v_mfma_f32_16x16x32_bf16 v[124:127], v[64:67], v[168:171], v[124:127]
	v_mfma_f32_16x16x32_bf16 v[120:123], v[72:75], v[168:171], v[120:123]
	v_mfma_f32_16x16x32_bf16 v[108:111], v[64:67], v[176:179], v[108:111]
	v_mfma_f32_16x16x32_bf16 v[104:107], v[72:75], v[176:179], v[104:107]
	v_mfma_f32_16x16x32_bf16 v[92:95], v[64:67], v[184:187], v[92:95]
	v_mfma_f32_16x16x32_bf16 v[88:91], v[72:75], v[184:187], v[88:91]
	v_mfma_f32_16x16x32_bf16 v[140:143], v[68:71], v[164:167], v[140:143]
	v_mfma_f32_16x16x32_bf16 v[136:139], v[76:79], v[164:167], v[136:139]
	v_mfma_f32_16x16x32_bf16 v[124:127], v[68:71], v[172:175], v[124:127]
	v_mfma_f32_16x16x32_bf16 v[120:123], v[76:79], v[172:175], v[120:123]
	v_mfma_f32_16x16x32_bf16 v[108:111], v[68:71], v[180:183], v[108:111]
	v_mfma_f32_16x16x32_bf16 v[104:107], v[76:79], v[180:183], v[104:107]
	v_mfma_f32_16x16x32_bf16 v[92:95], v[68:71], v[188:191], v[92:95]
	v_mfma_f32_16x16x32_bf16 v[88:91], v[76:79], v[188:191], v[88:91]
	s_setprio 0
	s_setprio 1
	v_mfma_f32_16x16x32_bf16 v[132:135], v[144:147], v[160:163], v[132:135]
	v_mfma_f32_16x16x32_bf16 v[128:131], v[152:155], v[160:163], v[128:131]
	v_mfma_f32_16x16x32_bf16 v[116:119], v[144:147], v[168:171], v[116:119]
	v_mfma_f32_16x16x32_bf16 v[112:115], v[152:155], v[168:171], v[112:115]
	v_mfma_f32_16x16x32_bf16 v[100:103], v[144:147], v[176:179], v[100:103]
	v_mfma_f32_16x16x32_bf16 v[96:99], v[152:155], v[176:179], v[96:99]
	v_mfma_f32_16x16x32_bf16 v[84:87], v[144:147], v[184:187], v[84:87]
	v_mfma_f32_16x16x32_bf16 v[80:83], v[152:155], v[184:187], v[80:83]
	v_mfma_f32_16x16x32_bf16 v[132:135], v[148:151], v[164:167], v[132:135]
	v_mfma_f32_16x16x32_bf16 v[128:131], v[156:159], v[164:167], v[128:131]
	v_mfma_f32_16x16x32_bf16 v[116:119], v[148:151], v[172:175], v[116:119]
	v_mfma_f32_16x16x32_bf16 v[112:115], v[156:159], v[172:175], v[112:115]
	v_mfma_f32_16x16x32_bf16 v[100:103], v[148:151], v[180:183], v[100:103]
	v_mfma_f32_16x16x32_bf16 v[96:99], v[156:159], v[180:183], v[96:99]
	v_mfma_f32_16x16x32_bf16 v[84:87], v[148:151], v[188:191], v[84:87]
	v_mfma_f32_16x16x32_bf16 v[80:83], v[156:159], v[188:191], v[80:83]
	s_setprio 0
	s_barrier
; #define PG8_STAGE(bufoff, gbase, voff) do { _Pragma("unroll") for (int _i = 0; _i < 2; ++_i) \
;         __builtin_amdgcn_global_load_lds((const unsigned*)((const char*)(gbase) + (voff)[_i]), (PG8_LAS unsigned*)(lds + (bufoff) + ldsw + _i * 8192), 16, 0, 0); } while (0)
; #define PG8_LDA(dst, b, h) do { _Pragma("unroll") for (int m = 0; m < 4; ++m) _Pragma("unroll") for (int k = 0; k < 2; ++k) dst[m][k] = *(const PG8_LAS bf16x8*)(lds + PG8_SA(b, h) + aoff + m * 2048 + k * 1024); } while (0)
; #define PG8_MMA(ai, bj, At, Bt) do { __builtin_amdgcn_s_setprio(1); _Pragma("unroll") for (int m = 0; m < 4; ++m) _Pragma("unroll") for (int n = 0; n < 2; ++n) _Pragma("unroll") for (int k = 0; k < 2; ++k) \
;         acc[ai][bj][m][n] = __builtin_amdgcn_mfma_f32_16x16x32_bf16(Bt[n][k], At[m][k], acc[ai][bj][m][n], 0, 0, 0); __builtin_amdgcn_s_setprio(0); } while (0)
; #define PG8_WAIT_V(n) asm volatile("s_waitcnt vmcnt(" #n ")" ::: "memory")
; #define PG8_WAIT_L(n) asm volatile("s_waitcnt lgkmcnt(" #n ")" ::: "memory")
; #define PG8_BAR __builtin_amdgcn_s_barrier()
; #define PG8_SCHED __builtin_amdgcn_sched_barrier(0)
; template <class Epi, class Sched, bool ALIGN_EPI = false, bool SP2 = false>
; __device__ __forceinline__ void gemm_phase(PG8_LAS unsigned char* lds, const Gemm g, const Sched& S, const Epi& E) {
;     ...
;         for (int t = 0; t < nt; t += 2) {
;     ...
;             PG8_LDA(At, 1, 1); PG8_STAGE(PG8_SB(1, 0), b3, voffB); PG8_STAGE(PG8_SB(1, 1), b3 + hstep, voffB); PG8_STAGE(PG8_SA(1, 0), a3, voffA);
;             PG8_WAIT_V(8); PG8_WAIT_L(0); PG8_BAR; PG8_MMA(1, 0, At, B0); PG8_MMA(1, 1, At, B1); PG8_BAR; PG8_SCHED;
	s_add_i32 s34, s72, s79
	v_lshl_add_u64 v[192:193], v[192:193], 0, s[8:9]
	s_mov_b32 m0, s34
	ds_read_b128 v[160:163], v241 offset:49152
	ds_read_b128 v[164:167], v241 offset:50176
	ds_read_b128 v[168:171], v241 offset:51200
	ds_read_b128 v[172:175], v241 offset:52224
	ds_read_b128 v[176:179], v241 offset:53248
	ds_read_b128 v[180:183], v241 offset:54272
	ds_read_b128 v[184:187], v241 offset:55296
	ds_read_b128 v[188:191], v241 offset:56320
	global_load_lds_dwordx4 v[192:193], off
	s_add_i32 m0, s34, 0x2000
	s_add_u32 s34, s62, 0x80080
	v_lshl_add_u64 v[192:193], v[194:195], 0, s[8:9]
	s_addc_u32 s35, s63, 0
	s_add_i32 s62, s74, s79
	global_load_lds_dwordx4 v[192:193], off
	v_lshl_add_u64 v[192:193], s[34:35], 0, v[204:205]
	s_mov_b32 m0, s62
	s_nop 0
	global_load_lds_dwordx4 v[192:193], off
	v_lshl_add_u64 v[192:193], s[34:35], 0, v[210:211]
	s_add_i32 m0, s62, 0x2000
	s_nop 0
	global_load_lds_dwordx4 v[192:193], off
	v_lshl_add_u64 v[192:193], v[196:197], 0, s[8:9]
	s_mov_b32 m0, s89
	s_nop 0
	global_load_lds_dwordx4 v[192:193], off
	v_lshl_add_u64 v[192:193], v[198:199], 0, s[8:9]
	s_mov_b32 m0, s90
	s_nop 0
	global_load_lds_dwordx4 v[192:193], off
	s_waitcnt vmcnt(8)
	s_waitcnt lgkmcnt(0)
	s_setprio 1
	s_barrier
	s_waitcnt lgkmcnt(0)
	v_mfma_f32_16x16x32_bf16 v[60:63], v[64:67], v[160:163], v[60:63]
	v_mfma_f32_16x16x32_bf16 v[56:59], v[72:75], v[160:163], v[56:59]
	v_mfma_f32_16x16x32_bf16 v[44:47], v[64:67], v[168:171], v[44:47]
	v_mfma_f32_16x16x32_bf16 v[40:43], v[72:75], v[168:171], v[40:43]
	v_mfma_f32_16x16x32_bf16 v[28:31], v[64:67], v[176:179], v[28:31]
	v_mfma_f32_16x16x32_bf16 v[24:27], v[72:75], v[176:179], v[24:27]
	v_mfma_f32_16x16x32_bf16 v[12:15], v[64:67], v[184:187], v[12:15]
	v_mfma_f32_16x16x32_bf16 v[8:11], v[72:75], v[184:187], v[8:11]
	v_mfma_f32_16x16x32_bf16 v[60:63], v[68:71], v[164:167], v[60:63]
	v_mfma_f32_16x16x32_bf16 v[56:59], v[76:79], v[164:167], v[56:59]
	v_mfma_f32_16x16x32_bf16 v[44:47], v[68:71], v[172:175], v[44:47]
	v_mfma_f32_16x16x32_bf16 v[40:43], v[76:79], v[172:175], v[40:43]
	v_mfma_f32_16x16x32_bf16 v[28:31], v[68:71], v[180:183], v[28:31]
	v_mfma_f32_16x16x32_bf16 v[24:27], v[76:79], v[180:183], v[24:27]
	v_mfma_f32_16x16x32_bf16 v[12:15], v[68:71], v[188:191], v[12:15]
	v_mfma_f32_16x16x32_bf16 v[8:11], v[76:79], v[188:191], v[8:11]
	s_setprio 0
	s_setprio 1
	v_mfma_f32_16x16x32_bf16 v[52:55], v[144:147], v[160:163], v[52:55]
	v_mfma_f32_16x16x32_bf16 v[48:51], v[152:155], v[160:163], v[48:51]
	v_mfma_f32_16x16x32_bf16 v[36:39], v[144:147], v[168:171], v[36:39]
	v_mfma_f32_16x16x32_bf16 v[32:35], v[152:155], v[168:171], v[32:35]
	v_mfma_f32_16x16x32_bf16 v[20:23], v[144:147], v[176:179], v[20:23]
	v_mfma_f32_16x16x32_bf16 v[16:19], v[152:155], v[176:179], v[16:19]
	v_mfma_f32_16x16x32_bf16 v[4:7], v[144:147], v[184:187], v[4:7]
	v_mfma_f32_16x16x32_bf16 v[0:3], v[152:155], v[184:187], v[0:3]
	v_mfma_f32_16x16x32_bf16 v[52:55], v[148:151], v[164:167], v[52:55]
	v_mfma_f32_16x16x32_bf16 v[48:51], v[156:159], v[164:167], v[48:51]
	v_mfma_f32_16x16x32_bf16 v[36:39], v[148:151], v[172:175], v[36:39]
	v_mfma_f32_16x16x32_bf16 v[32:35], v[156:159], v[172:175], v[32:35]
	v_mfma_f32_16x16x32_bf16 v[20:23], v[148:151], v[180:183], v[20:23]
	v_mfma_f32_16x16x32_bf16 v[16:19], v[156:159], v[180:183], v[16:19]
	v_mfma_f32_16x16x32_bf16 v[4:7], v[148:151], v[188:191], v[4:7]
	v_mfma_f32_16x16x32_bf16 v[0:3], v[156:159], v[188:191], v[0:3]
	s_setprio 0
	s_barrier
	s_add_i32 vcc_hi, vcc_hi, 2
	s_add_u32 s6, s6, 0x100
	s_addc_u32 s7, s7, 0
	s_add_u32 s99, s99, 0x100
	s_addc_u32 vcc_lo, vcc_lo, 0
	s_cmp_gt_u32 vcc_hi, 29
	s_cbranch_scc0 .LBB0_311
	s_and_b64 vcc, exec, s[10:11]
	s_cbranch_vccz .LBB0_314
	s_barrier

; #define PG8_STAGE(bufoff, gbase, voff) do { _Pragma("unroll") for (int _i = 0; _i < 2; ++_i) \
;         __builtin_amdgcn_global_load_lds((const unsigned*)((const char*)(gbase) + (voff)[_i]), (PG8_LAS unsigned*)(lds + (bufoff) + ldsw + _i * 8192), 16, 0, 0); } while (0)
; #define PG8_LDA(dst, b, h) do { _Pragma("unroll") for (int m = 0; m < 4; ++m) _Pragma("unroll") for (int k = 0; k < 2; ++k) dst[m][k] = *(const PG8_LAS bf16x8*)(lds + PG8_SA(b, h) + aoff + m * 2048 + k * 1024); } while (0)
; #define PG8_LDB(dst, b, h) do { _Pragma("unroll") for (int n = 0; n < 2; ++n) _Pragma("unroll") for (int k = 0; k < 2; ++k) dst[n][k] = *(const PG8_LAS bf16x8*)(lds + PG8_SB(b, h) + boff + n * 2048 + k * 1024); } while (0)
; #define PG8_MMA(ai, bj, At, Bt) do { __builtin_amdgcn_s_setprio(1); _Pragma("unroll") for (int m = 0; m < 4; ++m) _Pragma("unroll") for (int n = 0; n < 2; ++n) _Pragma("unroll") for (int k = 0; k < 2; ++k) \
;         acc[ai][bj][m][n] = __builtin_amdgcn_mfma_f32_16x16x32_bf16(Bt[n][k], At[m][k], acc[ai][bj][m][n], 0, 0, 0); __builtin_amdgcn_s_setprio(0); } while (0)
; #define PG8_WAIT_V(n) asm volatile("s_waitcnt vmcnt(" #n ")" ::: "memory")
; #define PG8_WAIT_L(n) asm volatile("s_waitcnt lgkmcnt(" #n ")" ::: "memory")
; template <class Epi, class Sched, bool ALIGN_EPI = false, bool SP2 = false>
; __device__ __forceinline__ void gemm_phase(PG8_LAS unsigned char* lds, const Gemm g, const Sched& S, const Epi& E) {
;     ...
;             const bool last = (t == nt - 2);
;             const char* a1 = cA + (size_t)(t + 1) * kstep;
;             const char* a2 = last ? nA : cA + (size_t)(t + 2) * kstep; const char* b2 = last ? nB : cB + (size_t)(t + 2) * kstep;
;             const char* a3 = a2 + kstep; const char* b3 = b2 + kstep;
;             if (last && has_next) S.a_ready(nxt);
;             if constexpr (SP2) {
;             PG8_LDB(B0, 0, 0); PG8_LDB(B1, 0, 1); PG8_SCHED; PG8_LDA(At, 0, 0); PG8_STAGE(PG8_SA(1, 1), a1 + hstep, voffA);
;             PG8_WAIT_V(8); PG8_WAIT_L(0); PG8_BAR; PG8_MMA(0, 0, At, B0); PG8_MMA(0, 1, At, B1); PG8_BAR; PG8_SCHED;
;             PG8_LDA(At, 0, 1); PG8_STAGE(PG8_SB(0, 0), b2, voffB); PG8_STAGE(PG8_SB(0, 1), b2 + hstep, voffB); PG8_STAGE(PG8_SA(0, 0), a2, voffA);
;             PG8_WAIT_V(8); PG8_WAIT_L(0); PG8_BAR; PG8_MMA(1, 0, At, B0); PG8_MMA(1, 1, At, B1); PG8_BAR; PG8_SCHED;
.LBB0_422:
	s_add_u32 s34, s60, 0xfff80080
	s_addc_u32 s35, s61, -1
	s_add_i32 s72, 0, 0x10000
	s_cmp_eq_u32 s93, 28
	s_cselect_b32 s67, s43, s35
	s_cselect_b32 s66, s89, s34
	v_add_u32_e32 v138, s72, v142
	s_cselect_b32 s63, s19, s92
	s_cselect_b32 s62, s90, s91
	s_add_i32 s74, 0, 0x14000
	ds_read_b128 v[144:147], v138
	ds_read_b128 v[148:151], v138 offset:1024
	ds_read_b128 v[152:155], v138 offset:2048
	ds_read_b128 v[156:159], v138 offset:3072
	v_add_u32_e32 v138, s74, v142
	ds_read_b128 v[160:163], v138
	ds_read_b128 v[164:167], v138 offset:1024
	ds_read_b128 v[168:171], v138 offset:2048
	ds_read_b128 v[172:175], v138 offset:3072
	v_lshl_add_u64 v[138:139], s[60:61], 0, v[134:135]
	s_add_i32 m0, s78, 0xc000
	ds_read_b128 v[176:179], v143
	ds_read_b128 v[180:183], v143 offset:1024
	ds_read_b128 v[184:187], v143 offset:2048
	ds_read_b128 v[188:191], v143 offset:3072
	ds_read_b128 v[192:195], v143 offset:4096
	ds_read_b128 v[196:199], v143 offset:5120
	ds_read_b128 v[200:203], v143 offset:6144
	ds_read_b128 v[206:209], v143 offset:7168
	global_load_lds_dwordx4 v[138:139], off
	v_lshl_add_u64 v[138:139], s[60:61], 0, v[136:137]
	s_add_i32 m0, s78, 0xe000
	s_nop 0
	global_load_lds_dwordx4 v[138:139], off
	s_waitcnt vmcnt(8)
	s_waitcnt lgkmcnt(0)
	s_setprio 1
	s_barrier
	s_waitcnt lgkmcnt(0)
	v_mfma_f32_16x16x32_bf16 v[124:127], v[144:147], v[176:179], v[124:127]
	v_mfma_f32_16x16x32_bf16 v[120:123], v[152:155], v[176:179], v[120:123]
	v_mfma_f32_16x16x32_bf16 v[108:111], v[144:147], v[184:187], v[108:111]
	v_mfma_f32_16x16x32_bf16 v[104:107], v[152:155], v[184:187], v[104:107]
	v_mfma_f32_16x16x32_bf16 v[92:95], v[144:147], v[192:195], v[92:95]
	v_mfma_f32_16x16x32_bf16 v[88:91], v[152:155], v[192:195], v[88:91]
	v_mfma_f32_16x16x32_bf16 v[76:79], v[144:147], v[200:203], v[76:79]
	v_mfma_f32_16x16x32_bf16 v[72:75], v[152:155], v[200:203], v[72:75]
	v_mfma_f32_16x16x32_bf16 v[124:127], v[148:151], v[180:183], v[124:127]
	v_mfma_f32_16x16x32_bf16 v[120:123], v[156:159], v[180:183], v[120:123]
	v_mfma_f32_16x16x32_bf16 v[108:111], v[148:151], v[188:191], v[108:111]
	v_mfma_f32_16x16x32_bf16 v[104:107], v[156:159], v[188:191], v[104:107]
	v_mfma_f32_16x16x32_bf16 v[92:95], v[148:151], v[196:199], v[92:95]
	v_mfma_f32_16x16x32_bf16 v[88:91], v[156:159], v[196:199], v[88:91]
	v_mfma_f32_16x16x32_bf16 v[76:79], v[148:151], v[206:209], v[76:79]
	v_mfma_f32_16x16x32_bf16 v[72:75], v[156:159], v[206:209], v[72:75]
	s_setprio 0
	s_setprio 1
	v_mfma_f32_16x16x32_bf16 v[116:119], v[160:163], v[176:179], v[116:119]
	v_mfma_f32_16x16x32_bf16 v[112:115], v[168:171], v[176:179], v[112:115]
	v_mfma_f32_16x16x32_bf16 v[100:103], v[160:163], v[184:187], v[100:103]
	v_mfma_f32_16x16x32_bf16 v[96:99], v[168:171], v[184:187], v[96:99]
	v_mfma_f32_16x16x32_bf16 v[84:87], v[160:163], v[192:195], v[84:87]
	v_mfma_f32_16x16x32_bf16 v[80:83], v[168:171], v[192:195], v[80:83]
	v_mfma_f32_16x16x32_bf16 v[68:71], v[160:163], v[200:203], v[68:71]
	v_mfma_f32_16x16x32_bf16 v[64:67], v[168:171], v[200:203], v[64:67]
	v_mfma_f32_16x16x32_bf16 v[116:119], v[164:167], v[180:183], v[116:119]
	v_mfma_f32_16x16x32_bf16 v[112:115], v[172:175], v[180:183], v[112:115]
	v_mfma_f32_16x16x32_bf16 v[100:103], v[164:167], v[188:191], v[100:103]
	v_mfma_f32_16x16x32_bf16 v[96:99], v[172:175], v[188:191], v[96:99]
	v_mfma_f32_16x16x32_bf16 v[84:87], v[164:167], v[196:199], v[84:87]
	v_mfma_f32_16x16x32_bf16 v[80:83], v[172:175], v[196:199], v[80:83]
	v_mfma_f32_16x16x32_bf16 v[68:71], v[164:167], v[206:209], v[68:71]
	v_mfma_f32_16x16x32_bf16 v[64:67], v[172:175], v[206:209], v[64:67]
	s_setprio 0
	s_barrier
	s_add_i32 s34, s72, s69
	v_lshl_add_u64 v[138:139], s[62:63], 0, v[204:205]
	s_mov_b32 m0, s34
	ds_read_b128 v[176:179], v143 offset:16384
	ds_read_b128 v[180:183], v143 offset:17408
	ds_read_b128 v[184:187], v143 offset:18432
	ds_read_b128 v[188:191], v143 offset:19456
	ds_read_b128 v[192:195], v143 offset:20480
	ds_read_b128 v[196:199], v143 offset:21504
	ds_read_b128 v[200:203], v143 offset:22528
	ds_read_b128 v[206:209], v143 offset:23552
	global_load_lds_dwordx4 v[138:139], off
	s_add_i32 m0, s34, 0x2000
	s_add_u32 s34, s62, 0x80000
	v_lshl_add_u64 v[210:211], s[62:63], 0, v[128:129]
	s_addc_u32 s35, s63, 0
	s_add_i32 s72, s74, s69
	global_load_lds_dwordx4 v[210:211], off
	v_lshl_add_u64 v[212:213], s[34:35], 0, v[204:205]
	s_mov_b32 m0, s72
	v_lshl_add_u64 v[214:215], s[66:67], 0, v[130:131]
	global_load_lds_dwordx4 v[212:213], off
	v_lshl_add_u64 v[212:213], s[34:35], 0, v[128:129]
	s_add_i32 m0, s72, 0x2000
	s_nop 0
	global_load_lds_dwordx4 v[212:213], off
	v_lshl_add_u64 v[212:213], s[66:67], 0, v[132:133]
	s_mov_b32 m0, s78
	s_nop 0
	global_load_lds_dwordx4 v[212:213], off
	s_mov_b32 m0, s79
	s_nop 0
	global_load_lds_dwordx4 v[214:215], off
	s_waitcnt vmcnt(8)
	s_waitcnt lgkmcnt(0)
	s_setprio 1
	s_barrier
; #define PG8_STAGE(bufoff, gbase, voff) do { _Pragma("unroll") for (int _i = 0; _i < 2; ++_i) \
;         __builtin_amdgcn_global_load_lds((const unsigned*)((const char*)(gbase) + (voff)[_i]), (PG8_LAS unsigned*)(lds + (bufoff) + ldsw + _i * 8192), 16, 0, 0); } while (0)
; #define PG8_LDA(dst, b, h) do { _Pragma("unroll") for (int m = 0; m < 4; ++m) _Pragma("unroll") for (int k = 0; k < 2; ++k) dst[m][k] = *(const PG8_LAS bf16x8*)(lds + PG8_SA(b, h) + aoff + m * 2048 + k * 1024); } while (0)
; #define PG8_LDB(dst, b, h) do { _Pragma("unroll") for (int n = 0; n < 2; ++n) _Pragma("unroll") for (int k = 0; k < 2; ++k) dst[n][k] = *(const PG8_LAS bf16x8*)(lds + PG8_SB(b, h) + boff + n * 2048 + k * 1024); } while (0)
; #define PG8_MMA(ai, bj, At, Bt) do { __builtin_amdgcn_s_setprio(1); _Pragma("unroll") for (int m = 0; m < 4; ++m) _Pragma("unroll") for (int n = 0; n < 2; ++n) _Pragma("unroll") for (int k = 0; k < 2; ++k) \
;         acc[ai][bj][m][n] = __builtin_amdgcn_mfma_f32_16x16x32_bf16(Bt[n][k], At[m][k], acc[ai][bj][m][n], 0, 0, 0); __builtin_amdgcn_s_setprio(0); } while (0)
; #define PG8_WAIT_V(n) asm volatile("s_waitcnt vmcnt(" #n ")" ::: "memory")
; #define PG8_WAIT_L(n) asm volatile("s_waitcnt lgkmcnt(" #n ")" ::: "memory")
; #define PG8_BAR __builtin_amdgcn_s_barrier()
; #define PG8_SCHED __builtin_amdgcn_sched_barrier(0)
; template <class Epi, class Sched, bool ALIGN_EPI = false, bool SP2 = false>
; __device__ __forceinline__ void gemm_phase(PG8_LAS unsigned char* lds, const Gemm g, const Sched& S, const Epi& E) {
;     ...
;             PG8_WAIT_V(8); PG8_WAIT_L(0); PG8_BAR; PG8_MMA(1, 0, At, B0); PG8_MMA(1, 1, At, B1); PG8_BAR; PG8_SCHED;
;             PG8_LDB(B0, 1, 0); PG8_LDB(B1, 1, 1); PG8_SCHED; PG8_LDA(At, 1, 0); PG8_STAGE(PG8_SA(0, 1), a2 + hstep, voffA);
;             PG8_WAIT_V(8); PG8_WAIT_L(0); PG8_BAR; PG8_MMA(0, 0, At, B0); PG8_MMA(0, 1, At, B1); PG8_BAR; PG8_SCHED;
	s_waitcnt lgkmcnt(0)
	v_mfma_f32_16x16x32_bf16 v[60:63], v[144:147], v[176:179], v[60:63]
	v_mfma_f32_16x16x32_bf16 v[56:59], v[152:155], v[176:179], v[56:59]
	v_mfma_f32_16x16x32_bf16 v[44:47], v[144:147], v[184:187], v[44:47]
	v_mfma_f32_16x16x32_bf16 v[40:43], v[152:155], v[184:187], v[40:43]
	v_mfma_f32_16x16x32_bf16 v[28:31], v[144:147], v[192:195], v[28:31]
	v_mfma_f32_16x16x32_bf16 v[24:27], v[152:155], v[192:195], v[24:27]
	v_mfma_f32_16x16x32_bf16 v[12:15], v[144:147], v[200:203], v[12:15]
	v_mfma_f32_16x16x32_bf16 v[8:11], v[152:155], v[200:203], v[8:11]
	v_mfma_f32_16x16x32_bf16 v[60:63], v[148:151], v[180:183], v[60:63]
	v_mfma_f32_16x16x32_bf16 v[56:59], v[156:159], v[180:183], v[56:59]
	v_mfma_f32_16x16x32_bf16 v[44:47], v[148:151], v[188:191], v[44:47]
	v_mfma_f32_16x16x32_bf16 v[40:43], v[156:159], v[188:191], v[40:43]
	v_mfma_f32_16x16x32_bf16 v[28:31], v[148:151], v[196:199], v[28:31]
	v_mfma_f32_16x16x32_bf16 v[24:27], v[156:159], v[196:199], v[24:27]
	v_mfma_f32_16x16x32_bf16 v[12:15], v[148:151], v[206:209], v[12:15]
	v_mfma_f32_16x16x32_bf16 v[8:11], v[156:159], v[206:209], v[8:11]
	s_setprio 0
	s_setprio 1
	v_mfma_f32_16x16x32_bf16 v[52:55], v[160:163], v[176:179], v[52:55]
	v_mfma_f32_16x16x32_bf16 v[48:51], v[168:171], v[176:179], v[48:51]
	v_mfma_f32_16x16x32_bf16 v[36:39], v[160:163], v[184:187], v[36:39]
	v_mfma_f32_16x16x32_bf16 v[32:35], v[168:171], v[184:187], v[32:35]
	v_mfma_f32_16x16x32_bf16 v[20:23], v[160:163], v[192:195], v[20:23]
	v_mfma_f32_16x16x32_bf16 v[16:19], v[168:171], v[192:195], v[16:19]
	v_mfma_f32_16x16x32_bf16 v[4:7], v[160:163], v[200:203], v[4:7]
	v_mfma_f32_16x16x32_bf16 v[0:3], v[168:171], v[200:203], v[0:3]
	v_mfma_f32_16x16x32_bf16 v[52:55], v[164:167], v[180:183], v[52:55]
	v_mfma_f32_16x16x32_bf16 v[48:51], v[172:175], v[180:183], v[48:51]
	v_mfma_f32_16x16x32_bf16 v[36:39], v[164:167], v[188:191], v[36:39]
	v_mfma_f32_16x16x32_bf16 v[32:35], v[172:175], v[188:191], v[32:35]
	v_mfma_f32_16x16x32_bf16 v[20:23], v[164:167], v[196:199], v[20:23]
	v_mfma_f32_16x16x32_bf16 v[16:19], v[172:175], v[196:199], v[16:19]
	v_mfma_f32_16x16x32_bf16 v[4:7], v[164:167], v[206:209], v[4:7]
	v_mfma_f32_16x16x32_bf16 v[0:3], v[172:175], v[206:209], v[0:3]
	s_setprio 0
	s_barrier
	s_add_i32 s72, 0, 0x18000
	s_add_i32 s74, 0, 0x1c000
	v_add_u32_e32 v156, s72, v142
	v_add_u32_e32 v172, s74, v142
	ds_read_b128 v[144:147], v156
	ds_read_b128 v[148:151], v156 offset:1024
	ds_read_b128 v[152:155], v156 offset:2048
	ds_read_b128 v[156:159], v156 offset:3072
	ds_read_b128 v[160:163], v172
	ds_read_b128 v[164:167], v172 offset:1024
	ds_read_b128 v[168:171], v172 offset:2048
	ds_read_b128 v[172:175], v172 offset:3072
	s_add_u32 s34, s66, 0x80000
	s_addc_u32 s35, s67, 0
	s_mov_b32 m0, s80
	v_lshl_add_u64 v[216:217], s[34:35], 0, v[132:133]
	ds_read_b128 v[176:179], v143 offset:32768
	ds_read_b128 v[180:183], v143 offset:33792
	ds_read_b128 v[184:187], v143 offset:34816
	ds_read_b128 v[188:191], v143 offset:35840
	ds_read_b128 v[192:195], v143 offset:36864
	ds_read_b128 v[196:199], v143 offset:37888
	ds_read_b128 v[200:203], v143 offset:38912
	ds_read_b128 v[206:209], v143 offset:39936
	global_load_lds_dwordx4 v[216:217], off
	v_lshl_add_u64 v[216:217], s[34:35], 0, v[130:131]
	s_mov_b32 m0, s81
	s_nop 0
	global_load_lds_dwordx4 v[216:217], off
	s_waitcnt vmcnt(8)
	s_waitcnt lgkmcnt(0)
	s_setprio 1
	s_barrier
	s_waitcnt lgkmcnt(0)
	v_mfma_f32_16x16x32_bf16 v[124:127], v[144:147], v[176:179], v[124:127]
	v_mfma_f32_16x16x32_bf16 v[120:123], v[152:155], v[176:179], v[120:123]
	v_mfma_f32_16x16x32_bf16 v[108:111], v[144:147], v[184:187], v[108:111]
	v_mfma_f32_16x16x32_bf16 v[104:107], v[152:155], v[184:187], v[104:107]
	v_mfma_f32_16x16x32_bf16 v[92:95], v[144:147], v[192:195], v[92:95]
	v_mfma_f32_16x16x32_bf16 v[88:91], v[152:155], v[192:195], v[88:91]
	v_mfma_f32_16x16x32_bf16 v[76:79], v[144:147], v[200:203], v[76:79]
	v_mfma_f32_16x16x32_bf16 v[72:75], v[152:155], v[200:203], v[72:75]
	v_mfma_f32_16x16x32_bf16 v[124:127], v[148:151], v[180:183], v[124:127]
	v_mfma_f32_16x16x32_bf16 v[120:123], v[156:159], v[180:183], v[120:123]
	v_mfma_f32_16x16x32_bf16 v[108:111], v[148:151], v[188:191], v[108:111]
	v_mfma_f32_16x16x32_bf16 v[104:107], v[156:159], v[188:191], v[104:107]
	v_mfma_f32_16x16x32_bf16 v[92:95], v[148:151], v[196:199], v[92:95]
	v_mfma_f32_16x16x32_bf16 v[88:91], v[156:159], v[196:199], v[88:91]
	v_mfma_f32_16x16x32_bf16 v[76:79], v[148:151], v[206:209], v[76:79]
	v_mfma_f32_16x16x32_bf16 v[72:75], v[156:159], v[206:209], v[72:75]
	s_setprio 0
	s_setprio 1
	v_mfma_f32_16x16x32_bf16 v[116:119], v[160:163], v[176:179], v[116:119]
	v_mfma_f32_16x16x32_bf16 v[112:115], v[168:171], v[176:179], v[112:115]
	v_mfma_f32_16x16x32_bf16 v[100:103], v[160:163], v[184:187], v[100:103]
	v_mfma_f32_16x16x32_bf16 v[96:99], v[168:171], v[184:187], v[96:99]
	v_mfma_f32_16x16x32_bf16 v[84:87], v[160:163], v[192:195], v[84:87]
	v_mfma_f32_16x16x32_bf16 v[80:83], v[168:171], v[192:195], v[80:83]
	v_mfma_f32_16x16x32_bf16 v[68:71], v[160:163], v[200:203], v[68:71]
	v_mfma_f32_16x16x32_bf16 v[64:67], v[168:171], v[200:203], v[64:67]
	v_mfma_f32_16x16x32_bf16 v[116:119], v[164:167], v[180:183], v[116:119]
	v_mfma_f32_16x16x32_bf16 v[112:115], v[172:175], v[180:183], v[112:115]
	v_mfma_f32_16x16x32_bf16 v[100:103], v[164:167], v[188:191], v[100:103]
	v_mfma_f32_16x16x32_bf16 v[96:99], v[172:175], v[188:191], v[96:99]
	v_mfma_f32_16x16x32_bf16 v[84:87], v[164:167], v[196:199], v[84:87]
	v_mfma_f32_16x16x32_bf16 v[80:83], v[172:175], v[196:199], v[80:83]
	v_mfma_f32_16x16x32_bf16 v[68:71], v[164:167], v[206:209], v[68:71]
	v_mfma_f32_16x16x32_bf16 v[64:67], v[172:175], v[206:209], v[64:67]
	s_setprio 0
	s_barrier
; #define PG8_STAGE(bufoff, gbase, voff) do { _Pragma("unroll") for (int _i = 0; _i < 2; ++_i) \
;         __builtin_amdgcn_global_load_lds((const unsigned*)((const char*)(gbase) + (voff)[_i]), (PG8_LAS unsigned*)(lds + (bufoff) + ldsw + _i * 8192), 16, 0, 0); } while (0)
; #define PG8_LDA(dst, b, h) do { _Pragma("unroll") for (int m = 0; m < 4; ++m) _Pragma("unroll") for (int k = 0; k < 2; ++k) dst[m][k] = *(const PG8_LAS bf16x8*)(lds + PG8_SA(b, h) + aoff + m * 2048 + k * 1024); } while (0)
; #define PG8_MMA(ai, bj, At, Bt) do { __builtin_amdgcn_s_setprio(1); _Pragma("unroll") for (int m = 0; m < 4; ++m) _Pragma("unroll") for (int n = 0; n < 2; ++n) _Pragma("unroll") for (int k = 0; k < 2; ++k) \
;         acc[ai][bj][m][n] = __builtin_amdgcn_mfma_f32_16x16x32_bf16(Bt[n][k], At[m][k], acc[ai][bj][m][n], 0, 0, 0); __builtin_amdgcn_s_setprio(0); } while (0)
; #define PG8_WAIT_V(n) asm volatile("s_waitcnt vmcnt(" #n ")" ::: "memory")
; #define PG8_WAIT_L(n) asm volatile("s_waitcnt lgkmcnt(" #n ")" ::: "memory")
; #define PG8_BAR __builtin_amdgcn_s_barrier()
; #define PG8_SCHED __builtin_amdgcn_sched_barrier(0)
; template <class Epi, class Sched, bool ALIGN_EPI = false, bool SP2 = false>
; __device__ __forceinline__ void gemm_phase(PG8_LAS unsigned char* lds, const Gemm g, const Sched& S, const Epi& E) {
;     ...
;         for (int t = 0; t < nt; t += 2) {
;     ...
;             PG8_LDA(At, 1, 1); PG8_STAGE(PG8_SB(1, 0), b3, voffB); PG8_STAGE(PG8_SB(1, 1), b3 + hstep, voffB); PG8_STAGE(PG8_SA(1, 0), a3, voffA);
;             PG8_WAIT_V(8); PG8_WAIT_L(0); PG8_BAR; PG8_MMA(1, 0, At, B0); PG8_MMA(1, 1, At, B1); PG8_BAR; PG8_SCHED;
	s_add_i32 s34, s72, s69
	v_lshl_add_u64 v[138:139], v[138:139], 0, s[8:9]
	s_mov_b32 m0, s34
	ds_read_b128 v[176:179], v143 offset:49152
	ds_read_b128 v[180:183], v143 offset:50176
	ds_read_b128 v[184:187], v143 offset:51200
	ds_read_b128 v[188:191], v143 offset:52224
	ds_read_b128 v[192:195], v143 offset:53248
	ds_read_b128 v[196:199], v143 offset:54272
	ds_read_b128 v[200:203], v143 offset:55296
	ds_read_b128 v[206:209], v143 offset:56320
	global_load_lds_dwordx4 v[138:139], off
	s_add_i32 m0, s34, 0x2000
	s_add_u32 s34, s62, 0x80080
	v_lshl_add_u64 v[138:139], v[210:211], 0, s[8:9]
	s_addc_u32 s35, s63, 0
	s_add_i32 s62, s74, s69
	global_load_lds_dwordx4 v[138:139], off
	v_lshl_add_u64 v[138:139], s[34:35], 0, v[204:205]
	s_mov_b32 m0, s62
	s_nop 0
	global_load_lds_dwordx4 v[138:139], off
	v_lshl_add_u64 v[138:139], s[34:35], 0, v[128:129]
	s_add_i32 m0, s62, 0x2000
	s_nop 0
	global_load_lds_dwordx4 v[138:139], off
	v_lshl_add_u64 v[138:139], v[212:213], 0, s[8:9]
	s_mov_b32 m0, s84
	s_nop 0
	global_load_lds_dwordx4 v[138:139], off
	v_lshl_add_u64 v[138:139], v[214:215], 0, s[8:9]
	s_mov_b32 m0, s85
	s_nop 0
	global_load_lds_dwordx4 v[138:139], off
	s_waitcnt vmcnt(8)
	s_waitcnt lgkmcnt(0)
	s_setprio 1
	s_barrier
	s_waitcnt lgkmcnt(0)
	v_mfma_f32_16x16x32_bf16 v[60:63], v[144:147], v[176:179], v[60:63]
	v_mfma_f32_16x16x32_bf16 v[56:59], v[152:155], v[176:179], v[56:59]
	v_mfma_f32_16x16x32_bf16 v[44:47], v[144:147], v[184:187], v[44:47]
	v_mfma_f32_16x16x32_bf16 v[40:43], v[152:155], v[184:187], v[40:43]
	v_mfma_f32_16x16x32_bf16 v[28:31], v[144:147], v[192:195], v[28:31]
	v_mfma_f32_16x16x32_bf16 v[24:27], v[152:155], v[192:195], v[24:27]
	v_mfma_f32_16x16x32_bf16 v[12:15], v[144:147], v[200:203], v[12:15]
	v_mfma_f32_16x16x32_bf16 v[8:11], v[152:155], v[200:203], v[8:11]
	v_mfma_f32_16x16x32_bf16 v[60:63], v[148:151], v[180:183], v[60:63]
	v_mfma_f32_16x16x32_bf16 v[56:59], v[156:159], v[180:183], v[56:59]
	v_mfma_f32_16x16x32_bf16 v[44:47], v[148:151], v[188:191], v[44:47]
	v_mfma_f32_16x16x32_bf16 v[40:43], v[156:159], v[188:191], v[40:43]
	v_mfma_f32_16x16x32_bf16 v[28:31], v[148:151], v[196:199], v[28:31]
	v_mfma_f32_16x16x32_bf16 v[24:27], v[156:159], v[196:199], v[24:27]
	v_mfma_f32_16x16x32_bf16 v[12:15], v[148:151], v[206:209], v[12:15]
	v_mfma_f32_16x16x32_bf16 v[8:11], v[156:159], v[206:209], v[8:11]
	s_setprio 0
	s_setprio 1
	v_mfma_f32_16x16x32_bf16 v[52:55], v[160:163], v[176:179], v[52:55]
	v_mfma_f32_16x16x32_bf16 v[48:51], v[168:171], v[176:179], v[48:51]
	v_mfma_f32_16x16x32_bf16 v[36:39], v[160:163], v[184:187], v[36:39]
	v_mfma_f32_16x16x32_bf16 v[32:35], v[168:171], v[184:187], v[32:35]
	v_mfma_f32_16x16x32_bf16 v[20:23], v[160:163], v[192:195], v[20:23]
	v_mfma_f32_16x16x32_bf16 v[16:19], v[168:171], v[192:195], v[16:19]
	v_mfma_f32_16x16x32_bf16 v[4:7], v[160:163], v[200:203], v[4:7]
	v_mfma_f32_16x16x32_bf16 v[0:3], v[168:171], v[200:203], v[0:3]
	v_mfma_f32_16x16x32_bf16 v[52:55], v[164:167], v[180:183], v[52:55]
	v_mfma_f32_16x16x32_bf16 v[48:51], v[172:175], v[180:183], v[48:51]
	v_mfma_f32_16x16x32_bf16 v[36:39], v[164:167], v[188:191], v[36:39]
	v_mfma_f32_16x16x32_bf16 v[32:35], v[172:175], v[188:191], v[32:35]
	v_mfma_f32_16x16x32_bf16 v[20:23], v[164:167], v[196:199], v[20:23]
	v_mfma_f32_16x16x32_bf16 v[16:19], v[172:175], v[196:199], v[16:19]
	v_mfma_f32_16x16x32_bf16 v[4:7], v[164:167], v[206:209], v[4:7]
	v_mfma_f32_16x16x32_bf16 v[0:3], v[172:175], v[206:209], v[0:3]
	s_setprio 0
	s_barrier
	s_add_i32 s93, s93, 2
	s_add_u32 s60, s60, 0x100
	s_addc_u32 s61, s61, 0
	s_add_u32 s91, s91, 0x100
	s_addc_u32 s92, s92, 0
	s_cmp_gt_u32 s93, 29
	s_cbranch_scc0 .LBB0_422
	s_and_b64 vcc, exec, s[10:11]
	s_cbranch_vccz .LBB0_425
	s_barrier

; #define PG8_STAGE(bufoff, gbase, voff) do { _Pragma("unroll") for (int _i = 0; _i < 2; ++_i) \
;         __builtin_amdgcn_global_load_lds((const unsigned*)((const char*)(gbase) + (voff)[_i]), (PG8_LAS unsigned*)(lds + (bufoff) + ldsw + _i * 8192), 16, 0, 0); } while (0)
; #define PG8_LDA(dst, b, h) do { _Pragma("unroll") for (int m = 0; m < 4; ++m) _Pragma("unroll") for (int k = 0; k < 2; ++k) dst[m][k] = *(const PG8_LAS bf16x8*)(lds + PG8_SA(b, h) + aoff + m * 2048 + k * 1024); } while (0)
; #define PG8_LDB(dst, b, h) do { _Pragma("unroll") for (int n = 0; n < 2; ++n) _Pragma("unroll") for (int k = 0; k < 2; ++k) dst[n][k] = *(const PG8_LAS bf16x8*)(lds + PG8_SB(b, h) + boff + n * 2048 + k * 1024); } while (0)
; #define PG8_MMA(ai, bj, At, Bt) do { __builtin_amdgcn_s_setprio(1); _Pragma("unroll") for (int m = 0; m < 4; ++m) _Pragma("unroll") for (int n = 0; n < 2; ++n) _Pragma("unroll") for (int k = 0; k < 2; ++k) \
;         acc[ai][bj][m][n] = __builtin_amdgcn_mfma_f32_16x16x32_bf16(Bt[n][k], At[m][k], acc[ai][bj][m][n], 0, 0, 0); __builtin_amdgcn_s_setprio(0); } while (0)
; #define PG8_WAIT_V(n) asm volatile("s_waitcnt vmcnt(" #n ")" ::: "memory")
; #define PG8_WAIT_L(n) asm volatile("s_waitcnt lgkmcnt(" #n ")" ::: "memory")
; template <class Epi, class Sched, bool ALIGN_EPI = false, bool SP2 = false>
; __device__ __forceinline__ void gemm_phase(PG8_LAS unsigned char* lds, const Gemm g, const Sched& S, const Epi& E) {
;     ...
;             const bool last = (t == nt - 2);
;             const char* a1 = cA + (size_t)(t + 1) * kstep;
;             const char* a2 = last ? nA : cA + (size_t)(t + 2) * kstep; const char* b2 = last ? nB : cB + (size_t)(t + 2) * kstep;
;             const char* a3 = a2 + kstep; const char* b3 = b2 + kstep;
;             if (last && has_next) S.a_ready(nxt);
;             if constexpr (SP2) {
;             PG8_LDB(B0, 0, 0); PG8_LDB(B1, 0, 1); PG8_SCHED; PG8_LDA(At, 0, 0); PG8_STAGE(PG8_SA(1, 1), a1 + hstep, voffA);
;             PG8_WAIT_V(8); PG8_WAIT_L(0); PG8_BAR; PG8_MMA(0, 0, At, B0); PG8_MMA(0, 1, At, B1); PG8_BAR; PG8_SCHED;
;             PG8_LDA(At, 0, 1); PG8_STAGE(PG8_SB(0, 0), b2, voffB); PG8_STAGE(PG8_SB(0, 1), b2 + hstep, voffB); PG8_STAGE(PG8_SA(0, 0), a2, voffA);
;             PG8_WAIT_V(8); PG8_WAIT_L(0); PG8_BAR; PG8_MMA(1, 0, At, B0); PG8_MMA(1, 1, At, B1); PG8_BAR; PG8_SCHED;
.LBB0_493:
	s_add_u32 s34, s4, 0xffe00080
	s_addc_u32 s35, s5, -1
	s_add_i32 s72, 0, 0x10000
	s_cmpk_eq_i32 vcc_hi, 0x7c
	s_cselect_b32 s69, s49, s35
	s_cselect_b32 s68, s92, s34
	s_cselect_b32 s67, s57, vcc_lo
	s_cselect_b32 s66, s93, s99
	s_add_i32 s74, 0, 0x14000
	v_add_u32_e32 v76, s72, v244
	v_add_u32_e32 v156, s74, v244
	ds_read_b128 v[64:67], v76
	ds_read_b128 v[68:71], v76 offset:1024
	ds_read_b128 v[72:75], v76 offset:2048
	ds_read_b128 v[76:79], v76 offset:3072
	ds_read_b128 v[144:147], v156
	ds_read_b128 v[148:151], v156 offset:1024
	ds_read_b128 v[152:155], v156 offset:2048
	ds_read_b128 v[156:159], v156 offset:3072
	v_lshl_add_u64 v[192:193], s[4:5], 0, v[216:217]
	s_add_i32 m0, s81, 0xc000
	ds_read_b128 v[160:163], v245
	ds_read_b128 v[164:167], v245 offset:1024
	ds_read_b128 v[168:171], v245 offset:2048
	ds_read_b128 v[172:175], v245 offset:3072
	ds_read_b128 v[176:179], v245 offset:4096
	ds_read_b128 v[180:183], v245 offset:5120
	ds_read_b128 v[184:187], v245 offset:6144
	ds_read_b128 v[188:191], v245 offset:7168
	global_load_lds_dwordx4 v[192:193], off
	v_lshl_add_u64 v[192:193], s[4:5], 0, v[218:219]
	s_add_i32 m0, s81, 0xe000
	s_nop 0
	global_load_lds_dwordx4 v[192:193], off
	s_waitcnt vmcnt(8)
	s_waitcnt lgkmcnt(0)
	s_setprio 1
	s_barrier
	s_waitcnt lgkmcnt(0)
	v_mfma_f32_16x16x32_bf16 v[140:143], v[64:67], v[160:163], v[140:143]
	v_mfma_f32_16x16x32_bf16 v[136:139], v[72:75], v[160:163], v[136:139]
	v_mfma_f32_16x16x32_bf16 v[124:127], v[64:67], v[168:171], v[124:127]
	v_mfma_f32_16x16x32_bf16 v[120:123], v[72:75], v[168:171], v[120:123]
	v_mfma_f32_16x16x32_bf16 v[108:111], v[64:67], v[176:179], v[108:111]
	v_mfma_f32_16x16x32_bf16 v[104:107], v[72:75], v[176:179], v[104:107]
	v_mfma_f32_16x16x32_bf16 v[92:95], v[64:67], v[184:187], v[92:95]
	v_mfma_f32_16x16x32_bf16 v[88:91], v[72:75], v[184:187], v[88:91]
	v_mfma_f32_16x16x32_bf16 v[140:143], v[68:71], v[164:167], v[140:143]
	v_mfma_f32_16x16x32_bf16 v[136:139], v[76:79], v[164:167], v[136:139]
	v_mfma_f32_16x16x32_bf16 v[124:127], v[68:71], v[172:175], v[124:127]
	v_mfma_f32_16x16x32_bf16 v[120:123], v[76:79], v[172:175], v[120:123]
	v_mfma_f32_16x16x32_bf16 v[108:111], v[68:71], v[180:183], v[108:111]
	v_mfma_f32_16x16x32_bf16 v[104:107], v[76:79], v[180:183], v[104:107]
	v_mfma_f32_16x16x32_bf16 v[92:95], v[68:71], v[188:191], v[92:95]
	v_mfma_f32_16x16x32_bf16 v[88:91], v[76:79], v[188:191], v[88:91]
	s_setprio 0
	s_setprio 1
	v_mfma_f32_16x16x32_bf16 v[132:135], v[144:147], v[160:163], v[132:135]
	v_mfma_f32_16x16x32_bf16 v[128:131], v[152:155], v[160:163], v[128:131]
	v_mfma_f32_16x16x32_bf16 v[116:119], v[144:147], v[168:171], v[116:119]
	v_mfma_f32_16x16x32_bf16 v[112:115], v[152:155], v[168:171], v[112:115]
	v_mfma_f32_16x16x32_bf16 v[100:103], v[144:147], v[176:179], v[100:103]
	v_mfma_f32_16x16x32_bf16 v[96:99], v[152:155], v[176:179], v[96:99]
	v_mfma_f32_16x16x32_bf16 v[84:87], v[144:147], v[184:187], v[84:87]
	v_mfma_f32_16x16x32_bf16 v[80:83], v[152:155], v[184:187], v[80:83]
	v_mfma_f32_16x16x32_bf16 v[132:135], v[148:151], v[164:167], v[132:135]
	v_mfma_f32_16x16x32_bf16 v[128:131], v[156:159], v[164:167], v[128:131]
	v_mfma_f32_16x16x32_bf16 v[116:119], v[148:151], v[172:175], v[116:119]
	v_mfma_f32_16x16x32_bf16 v[112:115], v[156:159], v[172:175], v[112:115]
	v_mfma_f32_16x16x32_bf16 v[100:103], v[148:151], v[180:183], v[100:103]
	v_mfma_f32_16x16x32_bf16 v[96:99], v[156:159], v[180:183], v[96:99]
	v_mfma_f32_16x16x32_bf16 v[84:87], v[148:151], v[188:191], v[84:87]
	v_mfma_f32_16x16x32_bf16 v[80:83], v[156:159], v[188:191], v[80:83]
	s_setprio 0
	s_barrier
	s_add_i32 s34, s72, s80
	v_lshl_add_u64 v[192:193], s[66:67], 0, v[204:205]
	s_mov_b32 m0, s34
	ds_read_b128 v[160:163], v245 offset:16384
	ds_read_b128 v[164:167], v245 offset:17408
	ds_read_b128 v[168:171], v245 offset:18432
	ds_read_b128 v[172:175], v245 offset:19456
	ds_read_b128 v[176:179], v245 offset:20480
	ds_read_b128 v[180:183], v245 offset:21504
	ds_read_b128 v[184:187], v245 offset:22528
	ds_read_b128 v[188:191], v245 offset:23552
	global_load_lds_dwordx4 v[192:193], off
	s_add_i32 m0, s34, 0x2000
	s_add_u32 s34, s66, 0x200000
	v_lshl_add_u64 v[194:195], s[66:67], 0, v[210:211]
	s_addc_u32 s35, s67, 0
	s_add_i32 s72, s74, s80
	global_load_lds_dwordx4 v[194:195], off
	v_lshl_add_u64 v[196:197], s[34:35], 0, v[204:205]
	s_mov_b32 m0, s72
	v_lshl_add_u64 v[198:199], s[68:69], 0, v[212:213]
	global_load_lds_dwordx4 v[196:197], off
	v_lshl_add_u64 v[196:197], s[34:35], 0, v[210:211]
	s_add_i32 m0, s72, 0x2000
	s_nop 0
	global_load_lds_dwordx4 v[196:197], off
	v_lshl_add_u64 v[196:197], s[68:69], 0, v[214:215]
	s_mov_b32 m0, s81
	s_nop 0
	global_load_lds_dwordx4 v[196:197], off
	s_mov_b32 m0, s82
	s_nop 0
	global_load_lds_dwordx4 v[198:199], off
	s_waitcnt vmcnt(8)
	s_waitcnt lgkmcnt(0)
	s_setprio 1
	s_barrier
; #define PG8_STAGE(bufoff, gbase, voff) do { _Pragma("unroll") for (int _i = 0; _i < 2; ++_i) \
;         __builtin_amdgcn_global_load_lds((const unsigned*)((const char*)(gbase) + (voff)[_i]), (PG8_LAS unsigned*)(lds + (bufoff) + ldsw + _i * 8192), 16, 0, 0); } while (0)
; #define PG8_LDA(dst, b, h) do { _Pragma("unroll") for (int m = 0; m < 4; ++m) _Pragma("unroll") for (int k = 0; k < 2; ++k) dst[m][k] = *(const PG8_LAS bf16x8*)(lds + PG8_SA(b, h) + aoff + m * 2048 + k * 1024); } while (0)
; #define PG8_LDB(dst, b, h) do { _Pragma("unroll") for (int n = 0; n < 2; ++n) _Pragma("unroll") for (int k = 0; k < 2; ++k) dst[n][k] = *(const PG8_LAS bf16x8*)(lds + PG8_SB(b, h) + boff + n * 2048 + k * 1024); } while (0)
; #define PG8_MMA(ai, bj, At, Bt) do { __builtin_amdgcn_s_setprio(1); _Pragma("unroll") for (int m = 0; m < 4; ++m) _Pragma("unroll") for (int n = 0; n < 2; ++n) _Pragma("unroll") for (int k = 0; k < 2; ++k) \
;         acc[ai][bj][m][n] = __builtin_amdgcn_mfma_f32_16x16x32_bf16(Bt[n][k], At[m][k], acc[ai][bj][m][n], 0, 0, 0); __builtin_amdgcn_s_setprio(0); } while (0)
; #define PG8_WAIT_V(n) asm volatile("s_waitcnt vmcnt(" #n ")" ::: "memory")
; #define PG8_WAIT_L(n) asm volatile("s_waitcnt lgkmcnt(" #n ")" ::: "memory")
; #define PG8_BAR __builtin_amdgcn_s_barrier()
; #define PG8_SCHED __builtin_amdgcn_sched_barrier(0)
; template <class Epi, class Sched, bool ALIGN_EPI = false, bool SP2 = false>
; __device__ __forceinline__ void gemm_phase(PG8_LAS unsigned char* lds, const Gemm g, const Sched& S, const Epi& E) {
;     ...
;             PG8_WAIT_V(8); PG8_WAIT_L(0); PG8_BAR; PG8_MMA(1, 0, At, B0); PG8_MMA(1, 1, At, B1); PG8_BAR; PG8_SCHED;
;             PG8_LDB(B0, 1, 0); PG8_LDB(B1, 1, 1); PG8_SCHED; PG8_LDA(At, 1, 0); PG8_STAGE(PG8_SA(0, 1), a2 + hstep, voffA);
;             PG8_WAIT_V(8); PG8_WAIT_L(0); PG8_BAR; PG8_MMA(0, 0, At, B0); PG8_MMA(0, 1, At, B1); PG8_BAR; PG8_SCHED;
	s_waitcnt lgkmcnt(0)
	v_mfma_f32_16x16x32_bf16 v[60:63], v[64:67], v[160:163], v[60:63]
	v_mfma_f32_16x16x32_bf16 v[56:59], v[72:75], v[160:163], v[56:59]
	v_mfma_f32_16x16x32_bf16 v[44:47], v[64:67], v[168:171], v[44:47]
	v_mfma_f32_16x16x32_bf16 v[40:43], v[72:75], v[168:171], v[40:43]
	v_mfma_f32_16x16x32_bf16 v[28:31], v[64:67], v[176:179], v[28:31]
	v_mfma_f32_16x16x32_bf16 v[24:27], v[72:75], v[176:179], v[24:27]
	v_mfma_f32_16x16x32_bf16 v[12:15], v[64:67], v[184:187], v[12:15]
	v_mfma_f32_16x16x32_bf16 v[8:11], v[72:75], v[184:187], v[8:11]
	v_mfma_f32_16x16x32_bf16 v[60:63], v[68:71], v[164:167], v[60:63]
	v_mfma_f32_16x16x32_bf16 v[56:59], v[76:79], v[164:167], v[56:59]
	v_mfma_f32_16x16x32_bf16 v[44:47], v[68:71], v[172:175], v[44:47]
	v_mfma_f32_16x16x32_bf16 v[40:43], v[76:79], v[172:175], v[40:43]
	v_mfma_f32_16x16x32_bf16 v[28:31], v[68:71], v[180:183], v[28:31]
	v_mfma_f32_16x16x32_bf16 v[24:27], v[76:79], v[180:183], v[24:27]
	v_mfma_f32_16x16x32_bf16 v[12:15], v[68:71], v[188:191], v[12:15]
	v_mfma_f32_16x16x32_bf16 v[8:11], v[76:79], v[188:191], v[8:11]
	s_setprio 0
	s_setprio 1
	v_mfma_f32_16x16x32_bf16 v[52:55], v[144:147], v[160:163], v[52:55]
	v_mfma_f32_16x16x32_bf16 v[48:51], v[152:155], v[160:163], v[48:51]
	v_mfma_f32_16x16x32_bf16 v[36:39], v[144:147], v[168:171], v[36:39]
	v_mfma_f32_16x16x32_bf16 v[32:35], v[152:155], v[168:171], v[32:35]
	v_mfma_f32_16x16x32_bf16 v[20:23], v[144:147], v[176:179], v[20:23]
	v_mfma_f32_16x16x32_bf16 v[16:19], v[152:155], v[176:179], v[16:19]
	v_mfma_f32_16x16x32_bf16 v[4:7], v[144:147], v[184:187], v[4:7]
	v_mfma_f32_16x16x32_bf16 v[0:3], v[152:155], v[184:187], v[0:3]
	v_mfma_f32_16x16x32_bf16 v[52:55], v[148:151], v[164:167], v[52:55]
	v_mfma_f32_16x16x32_bf16 v[48:51], v[156:159], v[164:167], v[48:51]
	v_mfma_f32_16x16x32_bf16 v[36:39], v[148:151], v[172:175], v[36:39]
	v_mfma_f32_16x16x32_bf16 v[32:35], v[156:159], v[172:175], v[32:35]
	v_mfma_f32_16x16x32_bf16 v[20:23], v[148:151], v[180:183], v[20:23]
	v_mfma_f32_16x16x32_bf16 v[16:19], v[156:159], v[180:183], v[16:19]
	v_mfma_f32_16x16x32_bf16 v[4:7], v[148:151], v[188:191], v[4:7]
	v_mfma_f32_16x16x32_bf16 v[0:3], v[156:159], v[188:191], v[0:3]
	s_setprio 0
	s_barrier
	s_add_i32 s72, 0, 0x18000
	s_add_i32 s74, 0, 0x1c000
	v_add_u32_e32 v76, s72, v244
	v_add_u32_e32 v156, s74, v244
	ds_read_b128 v[64:67], v76
	ds_read_b128 v[68:71], v76 offset:1024
	ds_read_b128 v[72:75], v76 offset:2048
	ds_read_b128 v[76:79], v76 offset:3072
	ds_read_b128 v[144:147], v156
	ds_read_b128 v[148:151], v156 offset:1024
	ds_read_b128 v[152:155], v156 offset:2048
	ds_read_b128 v[156:159], v156 offset:3072
	s_add_u32 s34, s68, 0x200000
	s_addc_u32 s35, s69, 0
	s_mov_b32 m0, s83
	v_lshl_add_u64 v[200:201], s[34:35], 0, v[214:215]
	ds_read_b128 v[160:163], v245 offset:32768
	ds_read_b128 v[164:167], v245 offset:33792
	ds_read_b128 v[168:171], v245 offset:34816
	ds_read_b128 v[172:175], v245 offset:35840
	ds_read_b128 v[176:179], v245 offset:36864
	ds_read_b128 v[180:183], v245 offset:37888
	ds_read_b128 v[184:187], v245 offset:38912
	ds_read_b128 v[188:191], v245 offset:39936
	global_load_lds_dwordx4 v[200:201], off
	v_lshl_add_u64 v[200:201], s[34:35], 0, v[212:213]
	s_mov_b32 m0, s84
	s_nop 0
	global_load_lds_dwordx4 v[200:201], off
	s_waitcnt vmcnt(8)
	s_waitcnt lgkmcnt(0)
	s_setprio 1
	s_barrier
	s_waitcnt lgkmcnt(0)
	v_mfma_f32_16x16x32_bf16 v[140:143], v[64:67], v[160:163], v[140:143]
	v_mfma_f32_16x16x32_bf16 v[136:139], v[72:75], v[160:163], v[136:139]
	v_mfma_f32_16x16x32_bf16 v[124:127], v[64:67], v[168:171], v[124:127]
	v_mfma_f32_16x16x32_bf16 v[120:123], v[72:75], v[168:171], v[120:123]
	v_mfma_f32_16x16x32_bf16 v[108:111], v[64:67], v[176:179], v[108:111]
	v_mfma_f32_16x16x32_bf16 v[104:107], v[72:75], v[176:179], v[104:107]
	v_mfma_f32_16x16x32_bf16 v[92:95], v[64:67], v[184:187], v[92:95]
	v_mfma_f32_16x16x32_bf16 v[88:91], v[72:75], v[184:187], v[88:91]
	v_mfma_f32_16x16x32_bf16 v[140:143], v[68:71], v[164:167], v[140:143]
	v_mfma_f32_16x16x32_bf16 v[136:139], v[76:79], v[164:167], v[136:139]
	v_mfma_f32_16x16x32_bf16 v[124:127], v[68:71], v[172:175], v[124:127]
	v_mfma_f32_16x16x32_bf16 v[120:123], v[76:79], v[172:175], v[120:123]
	v_mfma_f32_16x16x32_bf16 v[108:111], v[68:71], v[180:183], v[108:111]
	v_mfma_f32_16x16x32_bf16 v[104:107], v[76:79], v[180:183], v[104:107]
	v_mfma_f32_16x16x32_bf16 v[92:95], v[68:71], v[188:191], v[92:95]
	v_mfma_f32_16x16x32_bf16 v[88:91], v[76:79], v[188:191], v[88:91]
	s_setprio 0
	s_setprio 1
	v_mfma_f32_16x16x32_bf16 v[132:135], v[144:147], v[160:163], v[132:135]
	v_mfma_f32_16x16x32_bf16 v[128:131], v[152:155], v[160:163], v[128:131]
	v_mfma_f32_16x16x32_bf16 v[116:119], v[144:147], v[168:171], v[116:119]
	v_mfma_f32_16x16x32_bf16 v[112:115], v[152:155], v[168:171], v[112:115]
	v_mfma_f32_16x16x32_bf16 v[100:103], v[144:147], v[176:179], v[100:103]
	v_mfma_f32_16x16x32_bf16 v[96:99], v[152:155], v[176:179], v[96:99]
	v_mfma_f32_16x16x32_bf16 v[84:87], v[144:147], v[184:187], v[84:87]
	v_mfma_f32_16x16x32_bf16 v[80:83], v[152:155], v[184:187], v[80:83]
	v_mfma_f32_16x16x32_bf16 v[132:135], v[148:151], v[164:167], v[132:135]
	v_mfma_f32_16x16x32_bf16 v[128:131], v[156:159], v[164:167], v[128:131]
	v_mfma_f32_16x16x32_bf16 v[116:119], v[148:151], v[172:175], v[116:119]
	v_mfma_f32_16x16x32_bf16 v[112:115], v[156:159], v[172:175], v[112:115]
	v_mfma_f32_16x16x32_bf16 v[100:103], v[148:151], v[180:183], v[100:103]
	v_mfma_f32_16x16x32_bf16 v[96:99], v[156:159], v[180:183], v[96:99]
	v_mfma_f32_16x16x32_bf16 v[84:87], v[148:151], v[188:191], v[84:87]
	v_mfma_f32_16x16x32_bf16 v[80:83], v[156:159], v[188:191], v[80:83]
	s_setprio 0
	s_barrier
; #define PG8_STAGE(bufoff, gbase, voff) do { _Pragma("unroll") for (int _i = 0; _i < 2; ++_i) \
;         __builtin_amdgcn_global_load_lds((const unsigned*)((const char*)(gbase) + (voff)[_i]), (PG8_LAS unsigned*)(lds + (bufoff) + ldsw + _i * 8192), 16, 0, 0); } while (0)
; #define PG8_LDA(dst, b, h) do { _Pragma("unroll") for (int m = 0; m < 4; ++m) _Pragma("unroll") for (int k = 0; k < 2; ++k) dst[m][k] = *(const PG8_LAS bf16x8*)(lds + PG8_SA(b, h) + aoff + m * 2048 + k * 1024); } while (0)
; #define PG8_MMA(ai, bj, At, Bt) do { __builtin_amdgcn_s_setprio(1); _Pragma("unroll") for (int m = 0; m < 4; ++m) _Pragma("unroll") for (int n = 0; n < 2; ++n) _Pragma("unroll") for (int k = 0; k < 2; ++k) \
;         acc[ai][bj][m][n] = __builtin_amdgcn_mfma_f32_16x16x32_bf16(Bt[n][k], At[m][k], acc[ai][bj][m][n], 0, 0, 0); __builtin_amdgcn_s_setprio(0); } while (0)
; #define PG8_WAIT_V(n) asm volatile("s_waitcnt vmcnt(" #n ")" ::: "memory")
; #define PG8_WAIT_L(n) asm volatile("s_waitcnt lgkmcnt(" #n ")" ::: "memory")
; #define PG8_BAR __builtin_amdgcn_s_barrier()
; #define PG8_SCHED __builtin_amdgcn_sched_barrier(0)
; template <class Epi, class Sched, bool ALIGN_EPI = false, bool SP2 = false>
; __device__ __forceinline__ void gemm_phase(PG8_LAS unsigned char* lds, const Gemm g, const Sched& S, const Epi& E) {
;     ...
;         for (int t = 0; t < nt; t += 2) {
;     ...
;             PG8_LDA(At, 1, 1); PG8_STAGE(PG8_SB(1, 0), b3, voffB); PG8_STAGE(PG8_SB(1, 1), b3 + hstep, voffB); PG8_STAGE(PG8_SA(1, 0), a3, voffA);
;             PG8_WAIT_V(8); PG8_WAIT_L(0); PG8_BAR; PG8_MMA(1, 0, At, B0); PG8_MMA(1, 1, At, B1); PG8_BAR; PG8_SCHED;
	s_add_i32 s34, s72, s80
	v_lshl_add_u64 v[192:193], v[192:193], 0, s[8:9]
	s_mov_b32 m0, s34
	ds_read_b128 v[160:163], v245 offset:49152
	ds_read_b128 v[164:167], v245 offset:50176
	ds_read_b128 v[168:171], v245 offset:51200
	ds_read_b128 v[172:175], v245 offset:52224
	ds_read_b128 v[176:179], v245 offset:53248
	ds_read_b128 v[180:183], v245 offset:54272
	ds_read_b128 v[184:187], v245 offset:55296
	ds_read_b128 v[188:191], v245 offset:56320
	global_load_lds_dwordx4 v[192:193], off
	s_add_i32 m0, s34, 0x2000
	s_add_u32 s34, s66, 0x200080
	v_lshl_add_u64 v[192:193], v[194:195], 0, s[8:9]
	s_addc_u32 s35, s67, 0
	s_add_i32 s66, s74, s80
	global_load_lds_dwordx4 v[192:193], off
	v_lshl_add_u64 v[192:193], s[34:35], 0, v[204:205]
	s_mov_b32 m0, s66
	s_nop 0
	global_load_lds_dwordx4 v[192:193], off
	v_lshl_add_u64 v[192:193], s[34:35], 0, v[210:211]
	s_add_i32 m0, s66, 0x2000
	s_nop 0
	global_load_lds_dwordx4 v[192:193], off
	v_lshl_add_u64 v[192:193], v[196:197], 0, s[8:9]
	s_mov_b32 m0, s87
	s_nop 0
	global_load_lds_dwordx4 v[192:193], off
	v_lshl_add_u64 v[192:193], v[198:199], 0, s[8:9]
	s_mov_b32 m0, s88
	s_nop 0
	global_load_lds_dwordx4 v[192:193], off
	s_waitcnt vmcnt(8)
	s_waitcnt lgkmcnt(0)
	s_setprio 1
	s_barrier
	s_waitcnt lgkmcnt(0)
	v_mfma_f32_16x16x32_bf16 v[60:63], v[64:67], v[160:163], v[60:63]
	v_mfma_f32_16x16x32_bf16 v[56:59], v[72:75], v[160:163], v[56:59]
	v_mfma_f32_16x16x32_bf16 v[44:47], v[64:67], v[168:171], v[44:47]
	v_mfma_f32_16x16x32_bf16 v[40:43], v[72:75], v[168:171], v[40:43]
	v_mfma_f32_16x16x32_bf16 v[28:31], v[64:67], v[176:179], v[28:31]
	v_mfma_f32_16x16x32_bf16 v[24:27], v[72:75], v[176:179], v[24:27]
	v_mfma_f32_16x16x32_bf16 v[12:15], v[64:67], v[184:187], v[12:15]
	v_mfma_f32_16x16x32_bf16 v[8:11], v[72:75], v[184:187], v[8:11]
	v_mfma_f32_16x16x32_bf16 v[60:63], v[68:71], v[164:167], v[60:63]
	v_mfma_f32_16x16x32_bf16 v[56:59], v[76:79], v[164:167], v[56:59]
	v_mfma_f32_16x16x32_bf16 v[44:47], v[68:71], v[172:175], v[44:47]
	v_mfma_f32_16x16x32_bf16 v[40:43], v[76:79], v[172:175], v[40:43]
	v_mfma_f32_16x16x32_bf16 v[28:31], v[68:71], v[180:183], v[28:31]
	v_mfma_f32_16x16x32_bf16 v[24:27], v[76:79], v[180:183], v[24:27]
	v_mfma_f32_16x16x32_bf16 v[12:15], v[68:71], v[188:191], v[12:15]
	v_mfma_f32_16x16x32_bf16 v[8:11], v[76:79], v[188:191], v[8:11]
	s_setprio 0
	s_setprio 1
	v_mfma_f32_16x16x32_bf16 v[52:55], v[144:147], v[160:163], v[52:55]
	v_mfma_f32_16x16x32_bf16 v[48:51], v[152:155], v[160:163], v[48:51]
	v_mfma_f32_16x16x32_bf16 v[36:39], v[144:147], v[168:171], v[36:39]
	v_mfma_f32_16x16x32_bf16 v[32:35], v[152:155], v[168:171], v[32:35]
	v_mfma_f32_16x16x32_bf16 v[20:23], v[144:147], v[176:179], v[20:23]
	v_mfma_f32_16x16x32_bf16 v[16:19], v[152:155], v[176:179], v[16:19]
	v_mfma_f32_16x16x32_bf16 v[4:7], v[144:147], v[184:187], v[4:7]
	v_mfma_f32_16x16x32_bf16 v[0:3], v[152:155], v[184:187], v[0:3]
	v_mfma_f32_16x16x32_bf16 v[52:55], v[148:151], v[164:167], v[52:55]
	v_mfma_f32_16x16x32_bf16 v[48:51], v[156:159], v[164:167], v[48:51]
	v_mfma_f32_16x16x32_bf16 v[36:39], v[148:151], v[172:175], v[36:39]
	v_mfma_f32_16x16x32_bf16 v[32:35], v[156:159], v[172:175], v[32:35]
	v_mfma_f32_16x16x32_bf16 v[20:23], v[148:151], v[180:183], v[20:23]
	v_mfma_f32_16x16x32_bf16 v[16:19], v[156:159], v[180:183], v[16:19]
	v_mfma_f32_16x16x32_bf16 v[4:7], v[148:151], v[188:191], v[4:7]
	v_mfma_f32_16x16x32_bf16 v[0:3], v[156:159], v[188:191], v[0:3]
	s_setprio 0
	s_barrier
	s_add_i32 vcc_hi, vcc_hi, 2
	s_add_u32 s4, s4, 0x100
	s_addc_u32 s5, s5, 0
	s_add_u32 s99, s99, 0x100
	s_addc_u32 vcc_lo, vcc_lo, 0
	s_cmpk_gt_u32 vcc_hi, 0x7d
	s_cbranch_scc0 .LBB0_493
	s_and_b64 vcc, exec, s[10:11]
	s_cbranch_vccz .LBB0_496
	s_barrier
